# v9 + write-through (sc1) on the full-line x/xn store streams of the two residual phases
# speedup vs baseline: 1.0275x; 1.0275x over previous
.LBB0_698:
	v_mov_b32_e32 v12, v18
	v_mov_b32_e32 v13, v96
	v_lshlrev_b64 v[12:13], 11, v[12:13]
	v_lshl_add_u64 v[12:13], s[8:9], 0, v[12:13]
	v_lshl_add_u64 v[12:13], v[4:5], 1, v[12:13]
	s_mov_b32 s2, 0x40000
	s_mov_b32 s3, 0
	v_lshl_add_u64 v[14:15], v[12:13], 0, s[2:3]
	v_mul_lo_u32 v11, v17, s69
	v_lshl_add_u32 v11, v4, 1, v11
	global_load_dwordx4 v[186:189], v[12:13], off
	global_load_dwordx4 v[190:193], v[12:13], off offset:64
	global_load_dwordx4 v[194:197], v[12:13], off offset:128
	global_load_dwordx4 v[198:201], v[12:13], off offset:192
	global_load_dwordx4 v[202:205], v[12:13], off offset:256
	global_load_dwordx4 v[206:209], v[12:13], off offset:320
	global_load_dwordx4 v[210:213], v[12:13], off offset:384
	global_load_dwordx4 v[214:217], v[12:13], off offset:448
	global_load_dwordx4 v[218:221], v[12:13], off offset:512
	global_load_dwordx4 v[222:225], v[12:13], off offset:576
	global_load_dwordx4 v[226:229], v[12:13], off offset:640
	global_load_dwordx4 v[230:233], v[12:13], off offset:704
	global_load_dwordx4 v[236:239], v[12:13], off offset:768
	global_load_dwordx4 v[240:243], v[12:13], off offset:832
	global_load_dwordx4 v[244:247], v[12:13], off offset:896
	global_load_dwordx4 v[248:251], v[12:13], off offset:960
	ds_read_b128 v[48:51], v11
	ds_read_b128 v[52:55], v11 offset:64
	ds_read_b128 v[56:59], v11 offset:128
	ds_read_b128 v[60:63], v11 offset:192
	ds_read_b128 v[116:119], v11 offset:256
	ds_read_b128 v[120:123], v11 offset:320
	ds_read_b128 v[126:129], v11 offset:384
	ds_read_b128 v[130:133], v11 offset:448
	s_waitcnt vmcnt(8) lgkmcnt(0)
	v_mfma_f32_16x16x32_bf16 v[0:3], v[48:51], v[186:189], v[0:3]
	v_mfma_f32_16x16x32_bf16 v[0:3], v[52:55], v[190:193], v[0:3]
	v_mfma_f32_16x16x32_bf16 v[0:3], v[56:59], v[194:197], v[0:3]
	v_mfma_f32_16x16x32_bf16 v[0:3], v[60:63], v[198:201], v[0:3]
	v_mfma_f32_16x16x32_bf16 v[0:3], v[116:119], v[202:205], v[0:3]
	v_mfma_f32_16x16x32_bf16 v[0:3], v[120:123], v[206:209], v[0:3]
	v_mfma_f32_16x16x32_bf16 v[0:3], v[126:129], v[210:213], v[0:3]
	v_mfma_f32_16x16x32_bf16 v[0:3], v[130:133], v[214:217], v[0:3]
	global_load_dwordx4 v[186:189], v[12:13], off offset:1024
	global_load_dwordx4 v[190:193], v[12:13], off offset:1088
	global_load_dwordx4 v[194:197], v[12:13], off offset:1152
	global_load_dwordx4 v[198:201], v[12:13], off offset:1216
	global_load_dwordx4 v[202:205], v[12:13], off offset:1280
	global_load_dwordx4 v[206:209], v[12:13], off offset:1344
	global_load_dwordx4 v[210:213], v[12:13], off offset:1408
	global_load_dwordx4 v[214:217], v[12:13], off offset:1472
	ds_read_b128 v[48:51], v11 offset:512
	ds_read_b128 v[52:55], v11 offset:576
	ds_read_b128 v[56:59], v11 offset:640
	ds_read_b128 v[60:63], v11 offset:704
	ds_read_b128 v[116:119], v11 offset:768
	ds_read_b128 v[120:123], v11 offset:832
	ds_read_b128 v[126:129], v11 offset:896
	ds_read_b128 v[130:133], v11 offset:960
	s_waitcnt vmcnt(8) lgkmcnt(0)
	v_mfma_f32_16x16x32_bf16 v[0:3], v[48:51], v[218:221], v[0:3]
	v_mfma_f32_16x16x32_bf16 v[0:3], v[52:55], v[222:225], v[0:3]
	v_mfma_f32_16x16x32_bf16 v[0:3], v[56:59], v[226:229], v[0:3]
	v_mfma_f32_16x16x32_bf16 v[0:3], v[60:63], v[230:233], v[0:3]
	v_mfma_f32_16x16x32_bf16 v[0:3], v[116:119], v[236:239], v[0:3]
	v_mfma_f32_16x16x32_bf16 v[0:3], v[120:123], v[240:243], v[0:3]
	v_mfma_f32_16x16x32_bf16 v[0:3], v[126:129], v[244:247], v[0:3]
	v_mfma_f32_16x16x32_bf16 v[0:3], v[130:133], v[248:251], v[0:3]
	global_load_dwordx4 v[218:221], v[12:13], off offset:1536
	global_load_dwordx4 v[222:225], v[12:13], off offset:1600
	global_load_dwordx4 v[226:229], v[12:13], off offset:1664
	global_load_dwordx4 v[230:233], v[12:13], off offset:1728
	global_load_dwordx4 v[236:239], v[12:13], off offset:1792
	global_load_dwordx4 v[240:243], v[12:13], off offset:1856
	global_load_dwordx4 v[244:247], v[12:13], off offset:1920
	global_load_dwordx4 v[248:251], v[12:13], off offset:1984
	ds_read_b128 v[48:51], v11 offset:1024
	ds_read_b128 v[52:55], v11 offset:1088
	ds_read_b128 v[56:59], v11 offset:1152
	ds_read_b128 v[60:63], v11 offset:1216
	ds_read_b128 v[116:119], v11 offset:1280
	ds_read_b128 v[120:123], v11 offset:1344
	ds_read_b128 v[126:129], v11 offset:1408
	ds_read_b128 v[130:133], v11 offset:1472
	s_waitcnt vmcnt(8) lgkmcnt(0)
	v_mfma_f32_16x16x32_bf16 v[0:3], v[48:51], v[186:189], v[0:3]
	v_mfma_f32_16x16x32_bf16 v[0:3], v[52:55], v[190:193], v[0:3]
	v_mfma_f32_16x16x32_bf16 v[0:3], v[56:59], v[194:197], v[0:3]
	v_mfma_f32_16x16x32_bf16 v[0:3], v[60:63], v[198:201], v[0:3]
	v_mfma_f32_16x16x32_bf16 v[0:3], v[116:119], v[202:205], v[0:3]
	v_mfma_f32_16x16x32_bf16 v[0:3], v[120:123], v[206:209], v[0:3]
	v_mfma_f32_16x16x32_bf16 v[0:3], v[126:129], v[210:213], v[0:3]
	v_mfma_f32_16x16x32_bf16 v[0:3], v[130:133], v[214:217], v[0:3]
	global_load_dwordx4 v[186:189], v[14:15], off
	global_load_dwordx4 v[190:193], v[14:15], off offset:64
	global_load_dwordx4 v[194:197], v[14:15], off offset:128
	global_load_dwordx4 v[198:201], v[14:15], off offset:192
	global_load_dwordx4 v[202:205], v[14:15], off offset:256
	global_load_dwordx4 v[206:209], v[14:15], off offset:320
	global_load_dwordx4 v[210:213], v[14:15], off offset:384
	global_load_dwordx4 v[214:217], v[14:15], off offset:448
	ds_read_b128 v[48:51], v11 offset:1536
	ds_read_b128 v[52:55], v11 offset:1600
	ds_read_b128 v[56:59], v11 offset:1664
	ds_read_b128 v[60:63], v11 offset:1728
	ds_read_b128 v[116:119], v11 offset:1792
	ds_read_b128 v[120:123], v11 offset:1856
	ds_read_b128 v[126:129], v11 offset:1920
	ds_read_b128 v[130:133], v11 offset:1984
	s_waitcnt vmcnt(8) lgkmcnt(0)
	v_mfma_f32_16x16x32_bf16 v[0:3], v[48:51], v[218:221], v[0:3]
	v_mfma_f32_16x16x32_bf16 v[0:3], v[52:55], v[222:225], v[0:3]
	v_mfma_f32_16x16x32_bf16 v[0:3], v[56:59], v[226:229], v[0:3]
	v_mfma_f32_16x16x32_bf16 v[0:3], v[60:63], v[230:233], v[0:3]
	v_mfma_f32_16x16x32_bf16 v[0:3], v[116:119], v[236:239], v[0:3]
	v_mfma_f32_16x16x32_bf16 v[0:3], v[120:123], v[240:243], v[0:3]
	v_mfma_f32_16x16x32_bf16 v[0:3], v[126:129], v[244:247], v[0:3]
	v_mfma_f32_16x16x32_bf16 v[0:3], v[130:133], v[248:251], v[0:3]
	global_load_dwordx4 v[218:221], v[14:15], off offset:512
	global_load_dwordx4 v[222:225], v[14:15], off offset:576
	global_load_dwordx4 v[226:229], v[14:15], off offset:640
	global_load_dwordx4 v[230:233], v[14:15], off offset:704
	global_load_dwordx4 v[236:239], v[14:15], off offset:768
	global_load_dwordx4 v[240:243], v[14:15], off offset:832
	global_load_dwordx4 v[244:247], v[14:15], off offset:896
	global_load_dwordx4 v[248:251], v[14:15], off offset:960
	ds_read_b128 v[48:51], v11 offset:2064
	ds_read_b128 v[52:55], v11 offset:2128
	ds_read_b128 v[56:59], v11 offset:2192
	ds_read_b128 v[60:63], v11 offset:2256
	ds_read_b128 v[116:119], v11 offset:2320
	ds_read_b128 v[120:123], v11 offset:2384
	ds_read_b128 v[126:129], v11 offset:2448
	ds_read_b128 v[130:133], v11 offset:2512
	s_waitcnt vmcnt(8) lgkmcnt(0)
	v_mfma_f32_16x16x32_bf16 v[0:3], v[48:51], v[186:189], v[0:3]
	v_mfma_f32_16x16x32_bf16 v[0:3], v[52:55], v[190:193], v[0:3]
	v_mfma_f32_16x16x32_bf16 v[0:3], v[56:59], v[194:197], v[0:3]
	v_mfma_f32_16x16x32_bf16 v[0:3], v[60:63], v[198:201], v[0:3]
	v_mfma_f32_16x16x32_bf16 v[0:3], v[116:119], v[202:205], v[0:3]
	v_mfma_f32_16x16x32_bf16 v[0:3], v[120:123], v[206:209], v[0:3]
	v_mfma_f32_16x16x32_bf16 v[0:3], v[126:129], v[210:213], v[0:3]
	v_mfma_f32_16x16x32_bf16 v[0:3], v[130:133], v[214:217], v[0:3]
	global_load_dwordx4 v[186:189], v[14:15], off offset:1024
	global_load_dwordx4 v[190:193], v[14:15], off offset:1088
	global_load_dwordx4 v[194:197], v[14:15], off offset:1152
	global_load_dwordx4 v[198:201], v[14:15], off offset:1216
	global_load_dwordx4 v[202:205], v[14:15], off offset:1280
	global_load_dwordx4 v[206:209], v[14:15], off offset:1344
	global_load_dwordx4 v[210:213], v[14:15], off offset:1408
	global_load_dwordx4 v[214:217], v[14:15], off offset:1472
	ds_read_b128 v[48:51], v11 offset:2576
	ds_read_b128 v[52:55], v11 offset:2640
	ds_read_b128 v[56:59], v11 offset:2704
	ds_read_b128 v[60:63], v11 offset:2768
	ds_read_b128 v[116:119], v11 offset:2832
	ds_read_b128 v[120:123], v11 offset:2896
	ds_read_b128 v[126:129], v11 offset:2960
	ds_read_b128 v[130:133], v11 offset:3024
	s_waitcnt vmcnt(8) lgkmcnt(0)
	v_mfma_f32_16x16x32_bf16 v[0:3], v[48:51], v[218:221], v[0:3]
	v_mfma_f32_16x16x32_bf16 v[0:3], v[52:55], v[222:225], v[0:3]
	v_mfma_f32_16x16x32_bf16 v[0:3], v[56:59], v[226:229], v[0:3]
	v_mfma_f32_16x16x32_bf16 v[0:3], v[60:63], v[230:233], v[0:3]
	v_mfma_f32_16x16x32_bf16 v[0:3], v[116:119], v[236:239], v[0:3]
	v_mfma_f32_16x16x32_bf16 v[0:3], v[120:123], v[240:243], v[0:3]
	v_mfma_f32_16x16x32_bf16 v[0:3], v[126:129], v[244:247], v[0:3]
	v_mfma_f32_16x16x32_bf16 v[0:3], v[130:133], v[248:251], v[0:3]
	global_load_dwordx4 v[218:221], v[14:15], off offset:1536
	global_load_dwordx4 v[222:225], v[14:15], off offset:1600
	global_load_dwordx4 v[226:229], v[14:15], off offset:1664
	global_load_dwordx4 v[230:233], v[14:15], off offset:1728
	global_load_dwordx4 v[236:239], v[14:15], off offset:1792
	global_load_dwordx4 v[240:243], v[14:15], off offset:1856
	global_load_dwordx4 v[244:247], v[14:15], off offset:1920
	global_load_dwordx4 v[248:251], v[14:15], off offset:1984
	ds_read_b128 v[48:51], v11 offset:3088
	ds_read_b128 v[52:55], v11 offset:3152
	ds_read_b128 v[56:59], v11 offset:3216
	ds_read_b128 v[60:63], v11 offset:3280
	ds_read_b128 v[116:119], v11 offset:3344
	ds_read_b128 v[120:123], v11 offset:3408
	ds_read_b128 v[126:129], v11 offset:3472
	ds_read_b128 v[130:133], v11 offset:3536
	s_waitcnt vmcnt(8) lgkmcnt(0)
	v_mfma_f32_16x16x32_bf16 v[0:3], v[48:51], v[186:189], v[0:3]
	v_mfma_f32_16x16x32_bf16 v[0:3], v[52:55], v[190:193], v[0:3]
	v_mfma_f32_16x16x32_bf16 v[0:3], v[56:59], v[194:197], v[0:3]
	v_mfma_f32_16x16x32_bf16 v[0:3], v[60:63], v[198:201], v[0:3]
	v_mfma_f32_16x16x32_bf16 v[0:3], v[116:119], v[202:205], v[0:3]
	v_mfma_f32_16x16x32_bf16 v[0:3], v[120:123], v[206:209], v[0:3]
	v_mfma_f32_16x16x32_bf16 v[0:3], v[126:129], v[210:213], v[0:3]
	v_mfma_f32_16x16x32_bf16 v[0:3], v[130:133], v[214:217], v[0:3]
	ds_read_b128 v[48:51], v11 offset:3600
	ds_read_b128 v[52:55], v11 offset:3664
	ds_read_b128 v[56:59], v11 offset:3728
	ds_read_b128 v[60:63], v11 offset:3792
	ds_read_b128 v[116:119], v11 offset:3856
	ds_read_b128 v[120:123], v11 offset:3920
	ds_read_b128 v[126:129], v11 offset:3984
	ds_read_b128 v[130:133], v11 offset:4048
	s_waitcnt vmcnt(0) lgkmcnt(0)
	v_mfma_f32_16x16x32_bf16 v[0:3], v[48:51], v[218:221], v[0:3]
	v_mfma_f32_16x16x32_bf16 v[0:3], v[52:55], v[222:225], v[0:3]
	v_mfma_f32_16x16x32_bf16 v[0:3], v[56:59], v[226:229], v[0:3]
	v_mfma_f32_16x16x32_bf16 v[0:3], v[60:63], v[230:233], v[0:3]
	v_mfma_f32_16x16x32_bf16 v[0:3], v[116:119], v[236:239], v[0:3]
	v_mfma_f32_16x16x32_bf16 v[0:3], v[120:123], v[240:243], v[0:3]
	v_mfma_f32_16x16x32_bf16 v[0:3], v[126:129], v[244:247], v[0:3]
	v_mfma_f32_16x16x32_bf16 v[0:3], v[130:133], v[248:251], v[0:3]
	v_lshl_add_u32 v12, s16, 7, v18
	v_mov_b32_e32 v13, v96
	v_lshl_add_u64 v[12:13], v[12:13], 2, s[6:7]
	global_load_dword v11, v[12:13], off
	s_mov_b32 s9, 0x3fb8aa3b
	s_mov_b32 s16, 0xc2ce8ed0
	s_mov_b32 s17, 0x42b17218
	s_cmp_eq_u32 s26, 7
	s_cselect_b32 s8, 15, 16
	s_waitcnt vmcnt(0)
	v_add_f32_e32 v0, v0, v11
	v_mul_f32_e32 v12, 0x3d372713, v0
	v_mul_f32_e32 v12, v0, v12
	v_fma_f32 v12, v0, v12, v0
	v_mul_f32_e32 v12, 0x3f4c422a, v12
	v_add_f32_e32 v12, v12, v12
	v_mul_f32_e32 v13, 0x3fb8aa3b, v12
	v_fma_f32 v14, v12, s9, -v13
	v_rndne_f32_e32 v15, v13
	v_fmac_f32_e32 v14, 0x32a5705f, v12
	v_sub_f32_e32 v13, v13, v15
	v_add_f32_e32 v13, v13, v14
	v_exp_f32_e32 v13, v13
	v_cvt_i32_f32_e32 v14, v15
	v_cmp_ngt_f32_e32 vcc, s16, v12
	v_mul_f32_e32 v0, 0.5, v0
	v_add_f32_e32 v1, v1, v11
	v_ldexp_f32 v13, v13, v14
	v_cndmask_b32_e32 v13, 0, v13, vcc
	v_cmp_nlt_f32_e32 vcc, s17, v12
	s_nop 1
	v_cndmask_b32_e32 v12, v179, v13, vcc
	v_add_f32_e32 v12, 1.0, v12
	v_div_scale_f32 v13, s[2:3], v12, v12, 2.0
	v_rcp_f32_e32 v14, v13
	s_nop 0
	v_fma_f32 v15, -v13, v14, 1.0
	v_fmac_f32_e32 v14, v15, v14
	v_div_scale_f32 v15, vcc, 2.0, v12, 2.0
	v_mul_f32_e32 v23, v15, v14
	v_fma_f32 v24, -v13, v23, v15
	v_fmac_f32_e32 v23, v24, v14
	v_fma_f32 v13, -v13, v23, v15
	v_div_fmas_f32 v13, v13, v14, v23
	v_div_fixup_f32 v12, v13, v12, 2.0
	v_sub_f32_e32 v12, 1.0, v12
	v_add_f32_e32 v12, 1.0, v12
	v_mul_f32_e32 v0, v0, v12
	v_mul_f32_e32 v12, 0x3d372713, v1
	v_mul_f32_e32 v12, v1, v12
	v_fma_f32 v12, v1, v12, v1
	v_mul_f32_e32 v12, 0x3f4c422a, v12
	v_add_f32_e32 v12, v12, v12
	v_mul_f32_e32 v13, 0x3fb8aa3b, v12
	v_fma_f32 v14, v12, s9, -v13
	v_rndne_f32_e32 v15, v13
	v_fmac_f32_e32 v14, 0x32a5705f, v12
	v_sub_f32_e32 v13, v13, v15
	v_add_f32_e32 v13, v13, v14
	v_exp_f32_e32 v13, v13
	v_cvt_i32_f32_e32 v14, v15
	v_cmp_ngt_f32_e32 vcc, s16, v12
	v_mul_f32_e32 v1, 0.5, v1
	v_ldexp_f32 v13, v13, v14
	v_cndmask_b32_e32 v13, 0, v13, vcc
	v_cmp_nlt_f32_e32 vcc, s17, v12
	s_nop 1
	v_cndmask_b32_e32 v12, v179, v13, vcc
	v_add_f32_e32 v12, 1.0, v12
	v_div_scale_f32 v13, s[2:3], v12, v12, 2.0
	v_rcp_f32_e32 v14, v13
	s_nop 0
	v_fma_f32 v15, -v13, v14, 1.0
	v_fmac_f32_e32 v14, v15, v14
	v_div_scale_f32 v15, vcc, 2.0, v12, 2.0
	v_mul_f32_e32 v23, v15, v14
	v_fma_f32 v24, -v13, v23, v15
	v_fmac_f32_e32 v23, v24, v14
	v_fma_f32 v13, -v13, v23, v15
	v_div_fmas_f32 v13, v13, v14, v23
	v_div_fixup_f32 v12, v13, v12, 2.0
	v_sub_f32_e32 v12, 1.0, v12
	v_add_f32_e32 v12, 1.0, v12
	v_mul_f32_e32 v1, v1, v12
	ds_write2st64_b32 v19, v0, v1 offset0:144 offset1:146
	v_add_f32_e32 v0, v2, v11
	v_mul_f32_e32 v1, 0x3d372713, v0
	v_mul_f32_e32 v1, v0, v1
	v_fma_f32 v1, v0, v1, v0
	v_mul_f32_e32 v1, 0x3f4c422a, v1
	v_add_f32_e32 v1, v1, v1
	v_mul_f32_e32 v2, 0x3fb8aa3b, v1
	v_fma_f32 v12, v1, s9, -v2
	v_rndne_f32_e32 v13, v2
	v_fmac_f32_e32 v12, 0x32a5705f, v1
	v_sub_f32_e32 v2, v2, v13
	v_add_f32_e32 v2, v2, v12
	v_exp_f32_e32 v2, v2
	v_cvt_i32_f32_e32 v12, v13
	v_cmp_ngt_f32_e32 vcc, s16, v1
	v_mul_f32_e32 v0, 0.5, v0
	v_ldexp_f32 v2, v2, v12
	v_cndmask_b32_e32 v2, 0, v2, vcc
	v_cmp_nlt_f32_e32 vcc, s17, v1
	s_nop 1
	v_cndmask_b32_e32 v1, v179, v2, vcc
	v_add_f32_e32 v1, 1.0, v1
	v_div_scale_f32 v2, s[2:3], v1, v1, 2.0
	v_rcp_f32_e32 v12, v2
	s_nop 0
	v_fma_f32 v13, -v2, v12, 1.0
	v_fmac_f32_e32 v12, v13, v12
	v_div_scale_f32 v13, vcc, 2.0, v1, 2.0
	v_mul_f32_e32 v14, v13, v12
	v_fma_f32 v15, -v2, v14, v13
	v_fmac_f32_e32 v14, v15, v12
	v_fma_f32 v2, -v2, v14, v13
	v_div_fmas_f32 v2, v2, v12, v14
	v_div_fixup_f32 v1, v2, v1, 2.0
	v_sub_f32_e32 v1, 1.0, v1
	v_add_f32_e32 v1, 1.0, v1
	v_mul_f32_e32 v0, v0, v1
	v_add_f32_e32 v1, v3, v11
	v_mul_f32_e32 v2, 0x3d372713, v1
	v_mul_f32_e32 v2, v1, v2
	v_fma_f32 v2, v1, v2, v1
	v_mul_f32_e32 v2, 0x3f4c422a, v2
	v_add_f32_e32 v2, v2, v2
	v_mul_f32_e32 v3, 0x3fb8aa3b, v2
	v_fma_f32 v11, v2, s9, -v3
	v_rndne_f32_e32 v12, v3
	v_fmac_f32_e32 v11, 0x32a5705f, v2
	v_sub_f32_e32 v3, v3, v12
	v_add_f32_e32 v3, v3, v11
	v_exp_f32_e32 v3, v3
	v_cvt_i32_f32_e32 v11, v12
	v_cmp_ngt_f32_e32 vcc, s16, v2
	v_mul_f32_e32 v1, 0.5, v1
	v_ldexp_f32 v3, v3, v11
	v_cndmask_b32_e32 v3, 0, v3, vcc
	v_cmp_nlt_f32_e32 vcc, s17, v2
	s_nop 1
	v_cndmask_b32_e32 v2, v179, v3, vcc
	v_add_f32_e32 v2, 1.0, v2
	v_div_scale_f32 v3, s[2:3], v2, v2, 2.0
	v_rcp_f32_e32 v11, v3
	s_nop 0
	v_fma_f32 v12, -v3, v11, 1.0
	v_fmac_f32_e32 v11, v12, v11
	v_div_scale_f32 v12, vcc, 2.0, v2, 2.0
	v_mul_f32_e32 v13, v12, v11
	v_fma_f32 v14, -v3, v13, v12
	v_fmac_f32_e32 v13, v14, v11
	v_fma_f32 v3, -v3, v13, v12
	v_div_fmas_f32 v3, v3, v11, v13
	v_div_fixup_f32 v2, v3, v2, 2.0
	v_sub_f32_e32 v2, 1.0, v2
	v_add_f32_e32 v2, 1.0, v2
	v_mul_f32_e32 v1, v1, v2
	v_cmp_gt_i32_e32 vcc, s8, v20
	ds_write2st64_b32 v19, v0, v1 offset0:148 offset1:150
	s_waitcnt lgkmcnt(0)
	s_barrier
	s_and_saveexec_b64 s[8:9], vcc
	s_cbranch_execz .LBB0_691
	s_cmp_eq_u32 s30, 0
	s_cselect_b64 s[16:17], -1, 0
	s_and_b64 s[2:3], s[16:17], exec
	s_movk_i32 s2, 0xb8
	s_cselect_b32 s2, s2, 0xc0
	s_add_u32 s2, s10, s2
	s_addc_u32 s3, s11, 0
	s_load_dwordx2 s[2:3], s[2:3], 0x0
	v_mov_b32_e32 v2, 0
	s_mov_b64 s[18:19], 0
	v_mov_b32_e32 v11, v22
	v_mov_b32_e32 v3, v2
	s_waitcnt lgkmcnt(0)
	v_lshl_add_u64 v[0:1], s[2:3], 0, v[8:9]
.LBB0_701:
	s_mov_b32 s2, 0x1000
	s_mov_b32 s3, 0
	v_lshl_add_u64 v[12:13], v[0:1], 0, s[2:3]
	s_mov_b32 s2, 0x2000
	v_lshl_add_u64 v[14:15], v[12:13], 0, s[2:3]
	v_lshl_add_u64 v[24:25], v[14:15], 0, s[2:3]
	v_lshl_add_u64 v[26:27], v[24:25], 0, s[2:3]
	ds_read_b128 v[158:161], v22
	ds_read_b128 v[162:165], v22 offset:16
	ds_read_b128 v[166:169], v22 offset:32
	ds_read_b128 v[170:173], v22 offset:48
	global_load_dwordx2 v[186:187], v[12:13], off offset:-4096
	global_load_dwordx2 v[188:189], v[12:13], off offset:-3840
	global_load_dwordx2 v[190:191], v[12:13], off offset:-3584
	global_load_dwordx2 v[192:193], v[12:13], off offset:-3328
	global_load_dwordx2 v[194:195], v[12:13], off offset:-3072
	global_load_dwordx2 v[196:197], v[12:13], off offset:-2816
	global_load_dwordx2 v[198:199], v[12:13], off offset:-2560
	global_load_dwordx2 v[200:201], v[12:13], off offset:-2304
	global_load_dwordx2 v[202:203], v[12:13], off offset:-2048
	global_load_dwordx2 v[204:205], v[12:13], off offset:-1792
	global_load_dwordx2 v[206:207], v[12:13], off offset:-1536
	global_load_dwordx2 v[208:209], v[12:13], off offset:-1280
	global_load_dwordx2 v[210:211], v[12:13], off offset:-1024
	global_load_dwordx2 v[212:213], v[12:13], off offset:-768
	global_load_dwordx2 v[214:215], v[12:13], off offset:-512
	global_load_dwordx2 v[216:217], v[12:13], off offset:-256
	global_load_dwordx2 v[218:219], v[12:13], off
	global_load_dwordx2 v[220:221], v[12:13], off offset:256
	global_load_dwordx2 v[222:223], v[12:13], off offset:512
	global_load_dwordx2 v[224:225], v[12:13], off offset:768
	global_load_dwordx2 v[226:227], v[12:13], off offset:1024
	global_load_dwordx2 v[228:229], v[12:13], off offset:1280
	global_load_dwordx2 v[230:231], v[12:13], off offset:1536
	global_load_dwordx2 v[232:233], v[12:13], off offset:1792
	global_load_dwordx2 v[236:237], v[12:13], off offset:2048
	global_load_dwordx2 v[238:239], v[12:13], off offset:2304
	global_load_dwordx2 v[240:241], v[12:13], off offset:2560
	global_load_dwordx2 v[242:243], v[12:13], off offset:2816
	global_load_dwordx2 v[244:245], v[12:13], off offset:3072
	global_load_dwordx2 v[246:247], v[12:13], off offset:3328
	global_load_dwordx2 v[248:249], v[12:13], off offset:3584
	global_load_dwordx2 v[250:251], v[12:13], off offset:3840
	global_load_dwordx2 v[48:49], v[14:15], off offset:-4096
	global_load_dwordx2 v[50:51], v[14:15], off offset:-3840
	global_load_dwordx2 v[52:53], v[14:15], off offset:-3584
	global_load_dwordx2 v[54:55], v[14:15], off offset:-3328
	global_load_dwordx2 v[56:57], v[14:15], off offset:-3072
	global_load_dwordx2 v[58:59], v[14:15], off offset:-2816
	global_load_dwordx2 v[60:61], v[14:15], off offset:-2560
	global_load_dwordx2 v[62:63], v[14:15], off offset:-2304
	global_load_dwordx2 v[116:117], v[14:15], off offset:-2048
	global_load_dwordx2 v[118:119], v[14:15], off offset:-1792
	global_load_dwordx2 v[120:121], v[14:15], off offset:-1536
	global_load_dwordx2 v[122:123], v[14:15], off offset:-1280
	global_load_dwordx2 v[126:127], v[14:15], off offset:-1024
	global_load_dwordx2 v[128:129], v[14:15], off offset:-768
	global_load_dwordx2 v[130:131], v[14:15], off offset:-512
	global_load_dwordx2 v[132:133], v[14:15], off offset:-256
	ds_read_b128 v[136:139], v22 offset:64
	ds_read_b128 v[140:143], v22 offset:80
	ds_read_b128 v[148:151], v22 offset:96
	ds_read_b128 v[152:155], v22 offset:112
	s_waitcnt vmcnt(32) lgkmcnt(4)
	v_pk_fma_f32 v[2:3], v[158:159], v[186:187], v[2:3] op_sel_hi:[0,1,1]
	v_pk_fma_f32 v[2:3], v[158:159], v[188:189], v[2:3] op_sel:[1,0,0]
	v_pk_fma_f32 v[2:3], v[160:161], v[190:191], v[2:3] op_sel_hi:[0,1,1]
	v_pk_fma_f32 v[2:3], v[160:161], v[192:193], v[2:3] op_sel:[1,0,0]
	v_pk_fma_f32 v[2:3], v[162:163], v[194:195], v[2:3] op_sel_hi:[0,1,1]
	v_pk_fma_f32 v[2:3], v[162:163], v[196:197], v[2:3] op_sel:[1,0,0]
	v_pk_fma_f32 v[2:3], v[164:165], v[198:199], v[2:3] op_sel_hi:[0,1,1]
	v_pk_fma_f32 v[2:3], v[164:165], v[200:201], v[2:3] op_sel:[1,0,0]
	v_pk_fma_f32 v[2:3], v[166:167], v[202:203], v[2:3] op_sel_hi:[0,1,1]
	v_pk_fma_f32 v[2:3], v[166:167], v[204:205], v[2:3] op_sel:[1,0,0]
	v_pk_fma_f32 v[2:3], v[168:169], v[206:207], v[2:3] op_sel_hi:[0,1,1]
	v_pk_fma_f32 v[2:3], v[168:169], v[208:209], v[2:3] op_sel:[1,0,0]
	v_pk_fma_f32 v[2:3], v[170:171], v[210:211], v[2:3] op_sel_hi:[0,1,1]
	v_pk_fma_f32 v[2:3], v[170:171], v[212:213], v[2:3] op_sel:[1,0,0]
	v_pk_fma_f32 v[2:3], v[172:173], v[214:215], v[2:3] op_sel_hi:[0,1,1]
	v_pk_fma_f32 v[2:3], v[172:173], v[216:217], v[2:3] op_sel:[1,0,0]
	global_load_dwordx2 v[186:187], v[14:15], off
	global_load_dwordx2 v[188:189], v[14:15], off offset:256
	global_load_dwordx2 v[190:191], v[14:15], off offset:512
	global_load_dwordx2 v[192:193], v[14:15], off offset:768
	global_load_dwordx2 v[194:195], v[14:15], off offset:1024
	global_load_dwordx2 v[196:197], v[14:15], off offset:1280
	global_load_dwordx2 v[198:199], v[14:15], off offset:1536
	global_load_dwordx2 v[200:201], v[14:15], off offset:1792
	global_load_dwordx2 v[202:203], v[14:15], off offset:2048
	global_load_dwordx2 v[204:205], v[14:15], off offset:2304
	global_load_dwordx2 v[206:207], v[14:15], off offset:2560
	global_load_dwordx2 v[208:209], v[14:15], off offset:2816
	global_load_dwordx2 v[210:211], v[14:15], off offset:3072
	global_load_dwordx2 v[212:213], v[14:15], off offset:3328
	global_load_dwordx2 v[214:215], v[14:15], off offset:3584
	global_load_dwordx2 v[216:217], v[14:15], off offset:3840
	ds_read_b128 v[158:161], v22 offset:128
	ds_read_b128 v[162:165], v22 offset:144
	ds_read_b128 v[166:169], v22 offset:160
	ds_read_b128 v[170:173], v22 offset:176
	s_waitcnt vmcnt(32) lgkmcnt(4)
	v_pk_fma_f32 v[2:3], v[136:137], v[218:219], v[2:3] op_sel_hi:[0,1,1]
	v_pk_fma_f32 v[2:3], v[136:137], v[220:221], v[2:3] op_sel:[1,0,0]
	v_pk_fma_f32 v[2:3], v[138:139], v[222:223], v[2:3] op_sel_hi:[0,1,1]
	v_pk_fma_f32 v[2:3], v[138:139], v[224:225], v[2:3] op_sel:[1,0,0]
	v_pk_fma_f32 v[2:3], v[140:141], v[226:227], v[2:3] op_sel_hi:[0,1,1]
	v_pk_fma_f32 v[2:3], v[140:141], v[228:229], v[2:3] op_sel:[1,0,0]
	v_pk_fma_f32 v[2:3], v[142:143], v[230:231], v[2:3] op_sel_hi:[0,1,1]
	v_pk_fma_f32 v[2:3], v[142:143], v[232:233], v[2:3] op_sel:[1,0,0]
	v_pk_fma_f32 v[2:3], v[148:149], v[236:237], v[2:3] op_sel_hi:[0,1,1]
	v_pk_fma_f32 v[2:3], v[148:149], v[238:239], v[2:3] op_sel:[1,0,0]
	v_pk_fma_f32 v[2:3], v[150:151], v[240:241], v[2:3] op_sel_hi:[0,1,1]
	v_pk_fma_f32 v[2:3], v[150:151], v[242:243], v[2:3] op_sel:[1,0,0]
	v_pk_fma_f32 v[2:3], v[152:153], v[244:245], v[2:3] op_sel_hi:[0,1,1]
	v_pk_fma_f32 v[2:3], v[152:153], v[246:247], v[2:3] op_sel:[1,0,0]
	v_pk_fma_f32 v[2:3], v[154:155], v[248:249], v[2:3] op_sel_hi:[0,1,1]
	v_pk_fma_f32 v[2:3], v[154:155], v[250:251], v[2:3] op_sel:[1,0,0]
	global_load_dwordx2 v[218:219], v[24:25], off offset:-4096
	global_load_dwordx2 v[220:221], v[24:25], off offset:-3840
	global_load_dwordx2 v[222:223], v[24:25], off offset:-3584
	global_load_dwordx2 v[224:225], v[24:25], off offset:-3328
	global_load_dwordx2 v[226:227], v[24:25], off offset:-3072
	global_load_dwordx2 v[228:229], v[24:25], off offset:-2816
	global_load_dwordx2 v[230:231], v[24:25], off offset:-2560
	global_load_dwordx2 v[232:233], v[24:25], off offset:-2304
	global_load_dwordx2 v[236:237], v[24:25], off offset:-2048
	global_load_dwordx2 v[238:239], v[24:25], off offset:-1792
	global_load_dwordx2 v[240:241], v[24:25], off offset:-1536
	global_load_dwordx2 v[242:243], v[24:25], off offset:-1280
	global_load_dwordx2 v[244:245], v[24:25], off offset:-1024
	global_load_dwordx2 v[246:247], v[24:25], off offset:-768
	global_load_dwordx2 v[248:249], v[24:25], off offset:-512
	global_load_dwordx2 v[250:251], v[24:25], off offset:-256
	ds_read_b128 v[136:139], v22 offset:192
	ds_read_b128 v[140:143], v22 offset:208
	ds_read_b128 v[148:151], v22 offset:224
	ds_read_b128 v[152:155], v22 offset:240
	s_waitcnt vmcnt(32) lgkmcnt(4)
	v_pk_fma_f32 v[2:3], v[158:159], v[48:49], v[2:3] op_sel_hi:[0,1,1]
	v_pk_fma_f32 v[2:3], v[158:159], v[50:51], v[2:3] op_sel:[1,0,0]
	v_pk_fma_f32 v[2:3], v[160:161], v[52:53], v[2:3] op_sel_hi:[0,1,1]
	v_pk_fma_f32 v[2:3], v[160:161], v[54:55], v[2:3] op_sel:[1,0,0]
	v_pk_fma_f32 v[2:3], v[162:163], v[56:57], v[2:3] op_sel_hi:[0,1,1]
	v_pk_fma_f32 v[2:3], v[162:163], v[58:59], v[2:3] op_sel:[1,0,0]
	v_pk_fma_f32 v[2:3], v[164:165], v[60:61], v[2:3] op_sel_hi:[0,1,1]
	v_pk_fma_f32 v[2:3], v[164:165], v[62:63], v[2:3] op_sel:[1,0,0]
	v_pk_fma_f32 v[2:3], v[166:167], v[116:117], v[2:3] op_sel_hi:[0,1,1]
	v_pk_fma_f32 v[2:3], v[166:167], v[118:119], v[2:3] op_sel:[1,0,0]
	v_pk_fma_f32 v[2:3], v[168:169], v[120:121], v[2:3] op_sel_hi:[0,1,1]
	v_pk_fma_f32 v[2:3], v[168:169], v[122:123], v[2:3] op_sel:[1,0,0]
	v_pk_fma_f32 v[2:3], v[170:171], v[126:127], v[2:3] op_sel_hi:[0,1,1]
	v_pk_fma_f32 v[2:3], v[170:171], v[128:129], v[2:3] op_sel:[1,0,0]
	v_pk_fma_f32 v[2:3], v[172:173], v[130:131], v[2:3] op_sel_hi:[0,1,1]
	v_pk_fma_f32 v[2:3], v[172:173], v[132:133], v[2:3] op_sel:[1,0,0]
	global_load_dwordx2 v[48:49], v[24:25], off
	global_load_dwordx2 v[50:51], v[24:25], off offset:256
	global_load_dwordx2 v[52:53], v[24:25], off offset:512
	global_load_dwordx2 v[54:55], v[24:25], off offset:768
	global_load_dwordx2 v[56:57], v[24:25], off offset:1024
	global_load_dwordx2 v[58:59], v[24:25], off offset:1280
	global_load_dwordx2 v[60:61], v[24:25], off offset:1536
	global_load_dwordx2 v[62:63], v[24:25], off offset:1792
	global_load_dwordx2 v[116:117], v[24:25], off offset:2048
	global_load_dwordx2 v[118:119], v[24:25], off offset:2304
	global_load_dwordx2 v[120:121], v[24:25], off offset:2560
	global_load_dwordx2 v[122:123], v[24:25], off offset:2816
	global_load_dwordx2 v[126:127], v[24:25], off offset:3072
	global_load_dwordx2 v[128:129], v[24:25], off offset:3328
	global_load_dwordx2 v[130:131], v[24:25], off offset:3584
	global_load_dwordx2 v[132:133], v[24:25], off offset:3840
	ds_read_b128 v[158:161], v22 offset:256
	ds_read_b128 v[162:165], v22 offset:272
	ds_read_b128 v[166:169], v22 offset:288
	ds_read_b128 v[170:173], v22 offset:304
	s_waitcnt vmcnt(32) lgkmcnt(4)
	v_pk_fma_f32 v[2:3], v[136:137], v[186:187], v[2:3] op_sel_hi:[0,1,1]
	v_pk_fma_f32 v[2:3], v[136:137], v[188:189], v[2:3] op_sel:[1,0,0]
	v_pk_fma_f32 v[2:3], v[138:139], v[190:191], v[2:3] op_sel_hi:[0,1,1]
	v_pk_fma_f32 v[2:3], v[138:139], v[192:193], v[2:3] op_sel:[1,0,0]
	v_pk_fma_f32 v[2:3], v[140:141], v[194:195], v[2:3] op_sel_hi:[0,1,1]
	v_pk_fma_f32 v[2:3], v[140:141], v[196:197], v[2:3] op_sel:[1,0,0]
	v_pk_fma_f32 v[2:3], v[142:143], v[198:199], v[2:3] op_sel_hi:[0,1,1]
	v_pk_fma_f32 v[2:3], v[142:143], v[200:201], v[2:3] op_sel:[1,0,0]
	v_pk_fma_f32 v[2:3], v[148:149], v[202:203], v[2:3] op_sel_hi:[0,1,1]
	v_pk_fma_f32 v[2:3], v[148:149], v[204:205], v[2:3] op_sel:[1,0,0]
	v_pk_fma_f32 v[2:3], v[150:151], v[206:207], v[2:3] op_sel_hi:[0,1,1]
	v_pk_fma_f32 v[2:3], v[150:151], v[208:209], v[2:3] op_sel:[1,0,0]
	v_pk_fma_f32 v[2:3], v[152:153], v[210:211], v[2:3] op_sel_hi:[0,1,1]
	v_pk_fma_f32 v[2:3], v[152:153], v[212:213], v[2:3] op_sel:[1,0,0]
	v_pk_fma_f32 v[2:3], v[154:155], v[214:215], v[2:3] op_sel_hi:[0,1,1]
	v_pk_fma_f32 v[2:3], v[154:155], v[216:217], v[2:3] op_sel:[1,0,0]
	global_load_dwordx2 v[186:187], v[26:27], off offset:-4096
	global_load_dwordx2 v[188:189], v[26:27], off offset:-3840
	global_load_dwordx2 v[190:191], v[26:27], off offset:-3584
	global_load_dwordx2 v[192:193], v[26:27], off offset:-3328
	global_load_dwordx2 v[194:195], v[26:27], off offset:-3072
	global_load_dwordx2 v[196:197], v[26:27], off offset:-2816
	global_load_dwordx2 v[198:199], v[26:27], off offset:-2560
	global_load_dwordx2 v[200:201], v[26:27], off offset:-2304
	global_load_dwordx2 v[202:203], v[26:27], off offset:-2048
	global_load_dwordx2 v[204:205], v[26:27], off offset:-1792
	global_load_dwordx2 v[206:207], v[26:27], off offset:-1536
	global_load_dwordx2 v[208:209], v[26:27], off offset:-1280
	global_load_dwordx2 v[210:211], v[26:27], off offset:-1024
	global_load_dwordx2 v[212:213], v[26:27], off offset:-768
	global_load_dwordx2 v[214:215], v[26:27], off offset:-512
	global_load_dwordx2 v[216:217], v[26:27], off offset:-256
	ds_read_b128 v[136:139], v22 offset:320
	ds_read_b128 v[140:143], v22 offset:336
	ds_read_b128 v[148:151], v22 offset:352
	ds_read_b128 v[152:155], v22 offset:368
	s_waitcnt vmcnt(32) lgkmcnt(4)
	v_pk_fma_f32 v[2:3], v[158:159], v[218:219], v[2:3] op_sel_hi:[0,1,1]
	v_pk_fma_f32 v[2:3], v[158:159], v[220:221], v[2:3] op_sel:[1,0,0]
	v_pk_fma_f32 v[2:3], v[160:161], v[222:223], v[2:3] op_sel_hi:[0,1,1]
	v_pk_fma_f32 v[2:3], v[160:161], v[224:225], v[2:3] op_sel:[1,0,0]
	v_pk_fma_f32 v[2:3], v[162:163], v[226:227], v[2:3] op_sel_hi:[0,1,1]
	v_pk_fma_f32 v[2:3], v[162:163], v[228:229], v[2:3] op_sel:[1,0,0]
	v_pk_fma_f32 v[2:3], v[164:165], v[230:231], v[2:3] op_sel_hi:[0,1,1]
	v_pk_fma_f32 v[2:3], v[164:165], v[232:233], v[2:3] op_sel:[1,0,0]
	v_pk_fma_f32 v[2:3], v[166:167], v[236:237], v[2:3] op_sel_hi:[0,1,1]
	v_pk_fma_f32 v[2:3], v[166:167], v[238:239], v[2:3] op_sel:[1,0,0]
	v_pk_fma_f32 v[2:3], v[168:169], v[240:241], v[2:3] op_sel_hi:[0,1,1]
	v_pk_fma_f32 v[2:3], v[168:169], v[242:243], v[2:3] op_sel:[1,0,0]
	v_pk_fma_f32 v[2:3], v[170:171], v[244:245], v[2:3] op_sel_hi:[0,1,1]
	v_pk_fma_f32 v[2:3], v[170:171], v[246:247], v[2:3] op_sel:[1,0,0]
	v_pk_fma_f32 v[2:3], v[172:173], v[248:249], v[2:3] op_sel_hi:[0,1,1]
	v_pk_fma_f32 v[2:3], v[172:173], v[250:251], v[2:3] op_sel:[1,0,0]
	global_load_dwordx2 v[218:219], v[26:27], off
	global_load_dwordx2 v[220:221], v[26:27], off offset:256
	global_load_dwordx2 v[222:223], v[26:27], off offset:512
	global_load_dwordx2 v[224:225], v[26:27], off offset:768
	global_load_dwordx2 v[226:227], v[26:27], off offset:1024
	global_load_dwordx2 v[228:229], v[26:27], off offset:1280
	global_load_dwordx2 v[230:231], v[26:27], off offset:1536
	global_load_dwordx2 v[232:233], v[26:27], off offset:1792
	global_load_dwordx2 v[236:237], v[26:27], off offset:2048
	global_load_dwordx2 v[238:239], v[26:27], off offset:2304
	global_load_dwordx2 v[240:241], v[26:27], off offset:2560
	global_load_dwordx2 v[242:243], v[26:27], off offset:2816
	global_load_dwordx2 v[244:245], v[26:27], off offset:3072
	global_load_dwordx2 v[246:247], v[26:27], off offset:3328
	global_load_dwordx2 v[248:249], v[26:27], off offset:3584
	global_load_dwordx2 v[250:251], v[26:27], off offset:3840
	ds_read_b128 v[158:161], v22 offset:384
	ds_read_b128 v[162:165], v22 offset:400
	ds_read_b128 v[166:169], v22 offset:416
	ds_read_b128 v[170:173], v22 offset:432
	s_waitcnt vmcnt(32) lgkmcnt(4)
	v_pk_fma_f32 v[2:3], v[136:137], v[48:49], v[2:3] op_sel_hi:[0,1,1]
	v_pk_fma_f32 v[2:3], v[136:137], v[50:51], v[2:3] op_sel:[1,0,0]
	v_pk_fma_f32 v[2:3], v[138:139], v[52:53], v[2:3] op_sel_hi:[0,1,1]
	v_pk_fma_f32 v[2:3], v[138:139], v[54:55], v[2:3] op_sel:[1,0,0]
	v_pk_fma_f32 v[2:3], v[140:141], v[56:57], v[2:3] op_sel_hi:[0,1,1]
	v_pk_fma_f32 v[2:3], v[140:141], v[58:59], v[2:3] op_sel:[1,0,0]
	v_pk_fma_f32 v[2:3], v[142:143], v[60:61], v[2:3] op_sel_hi:[0,1,1]
	v_pk_fma_f32 v[2:3], v[142:143], v[62:63], v[2:3] op_sel:[1,0,0]
	v_pk_fma_f32 v[2:3], v[148:149], v[116:117], v[2:3] op_sel_hi:[0,1,1]
	v_pk_fma_f32 v[2:3], v[148:149], v[118:119], v[2:3] op_sel:[1,0,0]
	v_pk_fma_f32 v[2:3], v[150:151], v[120:121], v[2:3] op_sel_hi:[0,1,1]
	v_pk_fma_f32 v[2:3], v[150:151], v[122:123], v[2:3] op_sel:[1,0,0]
	v_pk_fma_f32 v[2:3], v[152:153], v[126:127], v[2:3] op_sel_hi:[0,1,1]
	v_pk_fma_f32 v[2:3], v[152:153], v[128:129], v[2:3] op_sel:[1,0,0]
	v_pk_fma_f32 v[2:3], v[154:155], v[130:131], v[2:3] op_sel_hi:[0,1,1]
	v_pk_fma_f32 v[2:3], v[154:155], v[132:133], v[2:3] op_sel:[1,0,0]
	ds_read_b128 v[136:139], v22 offset:448
	ds_read_b128 v[140:143], v22 offset:464
	ds_read_b128 v[148:151], v22 offset:480
	ds_read_b128 v[152:155], v22 offset:496
	s_waitcnt vmcnt(16) lgkmcnt(4)
	v_pk_fma_f32 v[2:3], v[158:159], v[186:187], v[2:3] op_sel_hi:[0,1,1]
	v_pk_fma_f32 v[2:3], v[158:159], v[188:189], v[2:3] op_sel:[1,0,0]
	v_pk_fma_f32 v[2:3], v[160:161], v[190:191], v[2:3] op_sel_hi:[0,1,1]
	v_pk_fma_f32 v[2:3], v[160:161], v[192:193], v[2:3] op_sel:[1,0,0]
	v_pk_fma_f32 v[2:3], v[162:163], v[194:195], v[2:3] op_sel_hi:[0,1,1]
	v_pk_fma_f32 v[2:3], v[162:163], v[196:197], v[2:3] op_sel:[1,0,0]
	v_pk_fma_f32 v[2:3], v[164:165], v[198:199], v[2:3] op_sel_hi:[0,1,1]
	v_pk_fma_f32 v[2:3], v[164:165], v[200:201], v[2:3] op_sel:[1,0,0]
	v_pk_fma_f32 v[2:3], v[166:167], v[202:203], v[2:3] op_sel_hi:[0,1,1]
	v_pk_fma_f32 v[2:3], v[166:167], v[204:205], v[2:3] op_sel:[1,0,0]
	v_pk_fma_f32 v[2:3], v[168:169], v[206:207], v[2:3] op_sel_hi:[0,1,1]
	v_pk_fma_f32 v[2:3], v[168:169], v[208:209], v[2:3] op_sel:[1,0,0]
	v_pk_fma_f32 v[2:3], v[170:171], v[210:211], v[2:3] op_sel_hi:[0,1,1]
	v_pk_fma_f32 v[2:3], v[170:171], v[212:213], v[2:3] op_sel:[1,0,0]
	v_pk_fma_f32 v[2:3], v[172:173], v[214:215], v[2:3] op_sel_hi:[0,1,1]
	v_pk_fma_f32 v[2:3], v[172:173], v[216:217], v[2:3] op_sel:[1,0,0]
	s_waitcnt vmcnt(0) lgkmcnt(0)
	v_pk_fma_f32 v[2:3], v[136:137], v[218:219], v[2:3] op_sel_hi:[0,1,1]
	v_pk_fma_f32 v[2:3], v[136:137], v[220:221], v[2:3] op_sel:[1,0,0]
	v_pk_fma_f32 v[2:3], v[138:139], v[222:223], v[2:3] op_sel_hi:[0,1,1]
	v_pk_fma_f32 v[2:3], v[138:139], v[224:225], v[2:3] op_sel:[1,0,0]
	v_pk_fma_f32 v[2:3], v[140:141], v[226:227], v[2:3] op_sel_hi:[0,1,1]
	v_pk_fma_f32 v[2:3], v[140:141], v[228:229], v[2:3] op_sel:[1,0,0]
	v_pk_fma_f32 v[2:3], v[142:143], v[230:231], v[2:3] op_sel_hi:[0,1,1]
	v_pk_fma_f32 v[2:3], v[142:143], v[232:233], v[2:3] op_sel:[1,0,0]
	v_pk_fma_f32 v[2:3], v[148:149], v[236:237], v[2:3] op_sel_hi:[0,1,1]
	v_pk_fma_f32 v[2:3], v[148:149], v[238:239], v[2:3] op_sel:[1,0,0]
	v_pk_fma_f32 v[2:3], v[150:151], v[240:241], v[2:3] op_sel_hi:[0,1,1]
	v_pk_fma_f32 v[2:3], v[150:151], v[242:243], v[2:3] op_sel:[1,0,0]
	v_pk_fma_f32 v[2:3], v[152:153], v[244:245], v[2:3] op_sel_hi:[0,1,1]
	v_pk_fma_f32 v[2:3], v[152:153], v[246:247], v[2:3] op_sel:[1,0,0]
	v_pk_fma_f32 v[2:3], v[154:155], v[248:249], v[2:3] op_sel_hi:[0,1,1]
	v_pk_fma_f32 v[2:3], v[154:155], v[250:251], v[2:3] op_sel:[1,0,0]
	s_and_b64 s[2:3], s[16:17], exec
	s_mov_b32 s2, 0x1ba00200
	s_cselect_b32 s2, s2, 0x1ba3fa00
	s_add_u32 s2, s14, s2
	s_addc_u32 s3, s15, 0
	s_mul_hi_i32 s16, s27, 0x7f00
	s_mulk_i32 s27, 0x7f00
	v_lshl_add_u32 v0, s26, 4, v20
	s_add_u32 s2, s2, s27
	v_ashrrev_i32_e32 v1, 31, v0
	s_addc_u32 s3, s3, s16
	v_lshlrev_b64 v[0:1], 8, v[0:1]
	v_lshl_add_u64 v[0:1], s[2:3], 0, v[0:1]
	v_mov_b32_e32 v11, v96
	v_lshl_add_u64 v[0:1], v[0:1], 0, v[10:11]
	global_store_dwordx2 v[0:1], v[2:3], off
	s_branch .LBB0_691

.LBB0_1440:
	s_ashr_i32 s17, s16, 31
	s_lshl_b64 s[18:19], s[16:17], 12
	s_waitcnt lgkmcnt(0)
	s_add_u32 s2, s4, s18
	s_addc_u32 s3, s5, s19
	s_lshl_b64 s[4:5], s[16:17], 11
	v_lshl_add_u64 v[4:5], v[82:83], 0, s[4:5]
	v_lshl_add_u64 v[28:29], v[80:81], 4, s[2:3]
	global_load_dwordx2 v[60:61], v[4:5], off
	global_load_dwordx4 v[40:43], v[28:29], off
	global_load_dwordx2 v[94:95], v[4:5], off offset:512
	global_load_dwordx4 v[24:27], v[28:29], off offset:1024
	global_load_dwordx2 v[92:93], v[4:5], off offset:1024
	global_load_dwordx4 v[12:15], v[28:29], off offset:2048
	global_load_dwordx2 v[74:75], v[4:5], off offset:1536
	global_load_dwordx4 v[0:3], v[28:29], off offset:3072
	global_load_dwordx2 v[72:73], v[4:5], off offset:2048
	v_add_co_u32_e32 v6, vcc, s79, v28
	s_movk_i32 s21, 0x2000
	s_nop 0
	v_addc_co_u32_e32 v7, vcc, 0, v29, vcc
	v_add_co_u32_e32 v30, vcc, s21, v28
	s_movk_i32 s22, 0x3000
	s_nop 0
	v_addc_co_u32_e32 v31, vcc, 0, v29, vcc
	global_load_dwordx4 v[48:51], v[30:31], off offset:-4096
	global_load_dwordx2 v[106:107], v[4:5], off offset:2560
	global_load_dwordx4 v[32:35], v[6:7], off offset:1024
	global_load_dwordx2 v[112:113], v[4:5], off offset:3072
	global_load_dwordx4 v[16:19], v[6:7], off offset:2048
	global_load_dwordx2 v[108:109], v[4:5], off offset:3584
	global_load_dwordx4 v[8:11], v[6:7], off offset:3072
	v_add_co_u32_e32 v62, vcc, s79, v4
	v_lshl_add_u64 v[160:161], v[86:87], 0, s[18:19]
	s_nop 0
	v_addc_co_u32_e32 v63, vcc, 0, v5, vcc
	global_load_dwordx2 v[110:111], v[62:63], off
	global_load_dwordx4 v[52:55], v[30:31], off
	global_load_dwordx2 v[78:79], v[62:63], off offset:512
	global_load_dwordx4 v[36:39], v[30:31], off offset:1024
	global_load_dwordx2 v[76:77], v[62:63], off offset:1024
	global_load_dwordx4 v[20:23], v[30:31], off offset:2048
	global_load_dwordx2 v[70:71], v[62:63], off offset:1536
	global_load_dwordx4 v[4:7], v[30:31], off offset:3072
	global_load_dwordx2 v[68:69], v[62:63], off offset:2048
	v_add_co_u32_e32 v28, vcc, s22, v28
	s_waitcnt vmcnt(0)
	v_and_b32_e32 v103, 0xffff0000, v94
	v_addc_co_u32_e32 v29, vcc, 0, v29, vcc
	global_load_dwordx4 v[64:67], v[28:29], off
	global_load_dwordx2 v[118:119], v[62:63], off offset:2560
	global_load_dwordx4 v[56:59], v[28:29], off offset:1024
	global_load_dwordx2 v[132:133], v[62:63], off offset:3072
	global_load_dwordx4 v[44:47], v[28:29], off offset:2048
	global_load_dwordx2 v[120:121], v[62:63], off offset:3584
	s_nop 0
	global_load_dwordx4 v[28:31], v[28:29], off offset:3072
	v_lshlrev_b32_e32 v62, 16, v60
	v_and_b32_e32 v63, 0xffff0000, v60
	v_lshlrev_b32_e32 v60, 16, v61
	v_and_b32_e32 v61, 0xffff0000, v61
	v_and_b32_e32 v105, 0xffff0000, v95
	v_mul_f32_e32 v98, v63, v63
	v_mul_f32_e32 v99, v61, v61
	v_lshlrev_b32_e32 v102, 16, v94
	v_lshlrev_b32_e32 v104, 16, v95
	v_mul_f32_e32 v94, v103, v103
	v_mul_f32_e32 v95, v105, v105
	v_fmac_f32_e32 v98, v62, v62
	v_fmac_f32_e32 v99, v60, v60
	v_fmac_f32_e32 v94, v102, v102
	v_fmac_f32_e32 v95, v104, v104
	v_add_f32_e32 v98, v98, v99
	v_add_f32_e32 v94, v94, v95
	v_and_b32_e32 v99, 0xffff0000, v92
	v_and_b32_e32 v101, 0xffff0000, v93
	v_add_f32_e32 v94, v98, v94
	v_lshlrev_b32_e32 v98, 16, v92
	v_lshlrev_b32_e32 v100, 16, v93
	v_mul_f32_e32 v92, v99, v99
	v_mul_f32_e32 v93, v101, v101
	v_fmac_f32_e32 v92, v98, v98
	v_fmac_f32_e32 v93, v100, v100
	v_add_f32_e32 v92, v92, v93
	v_and_b32_e32 v93, 0xffff0000, v74
	v_and_b32_e32 v95, 0xffff0000, v75
	v_add_f32_e32 v114, v94, v92
	v_lshlrev_b32_e32 v92, 16, v74
	v_lshlrev_b32_e32 v94, 16, v75
	v_mul_f32_e32 v74, v93, v93
	v_mul_f32_e32 v75, v95, v95
	v_fmac_f32_e32 v74, v92, v92
	v_fmac_f32_e32 v75, v94, v94
	v_add_f32_e32 v74, v74, v75
	v_add_f32_e32 v152, v114, v74
	v_lshlrev_b32_e32 v74, 16, v72
	v_and_b32_e32 v75, 0xffff0000, v72
	v_lshlrev_b32_e32 v72, 16, v73
	v_and_b32_e32 v73, 0xffff0000, v73
	v_and_b32_e32 v127, 0xffff0000, v106
	v_and_b32_e32 v129, 0xffff0000, v107
	v_mul_f32_e32 v114, v75, v75
	v_mul_f32_e32 v115, v73, v73
	v_lshlrev_b32_e32 v126, 16, v106
	v_lshlrev_b32_e32 v128, 16, v107
	v_mul_f32_e32 v106, v127, v127
	v_mul_f32_e32 v107, v129, v129
	v_fmac_f32_e32 v114, v74, v74
	v_fmac_f32_e32 v115, v72, v72
	v_fmac_f32_e32 v106, v126, v126
	v_fmac_f32_e32 v107, v128, v128
	v_add_f32_e32 v114, v114, v115
	v_add_f32_e32 v106, v106, v107
	v_and_b32_e32 v115, 0xffff0000, v112
	v_and_b32_e32 v117, 0xffff0000, v113
	v_add_f32_e32 v106, v114, v106
	v_lshlrev_b32_e32 v114, 16, v112
	v_lshlrev_b32_e32 v116, 16, v113
	v_mul_f32_e32 v107, v115, v115
	v_mul_f32_e32 v112, v117, v117
	v_fmac_f32_e32 v107, v114, v114
	v_fmac_f32_e32 v112, v116, v116
	v_add_f32_e32 v107, v107, v112
	v_add_f32_e32 v112, v106, v107
	v_lshlrev_b32_e32 v106, 16, v108
	v_and_b32_e32 v107, 0xffff0000, v108
	v_lshlrev_b32_e32 v108, 16, v109
	v_and_b32_e32 v109, 0xffff0000, v109
	v_mul_f32_e32 v113, v107, v107
	v_mul_f32_e32 v122, v109, v109
	v_and_b32_e32 v145, 0xffff0000, v110
	v_and_b32_e32 v143, 0xffff0000, v111
	v_and_b32_e32 v135, 0xffff0000, v78
	v_and_b32_e32 v137, 0xffff0000, v79
	v_fmac_f32_e32 v113, v106, v106
	v_fmac_f32_e32 v122, v108, v108
	v_lshlrev_b32_e32 v144, 16, v110
	v_lshlrev_b32_e32 v142, 16, v111
	v_mul_f32_e32 v110, v145, v145
	v_mul_f32_e32 v111, v143, v143
	v_lshlrev_b32_e32 v134, 16, v78
	v_lshlrev_b32_e32 v136, 16, v79
	v_mul_f32_e32 v78, v135, v135
	v_mul_f32_e32 v79, v137, v137
	v_add_f32_e32 v113, v113, v122
	v_fmac_f32_e32 v110, v144, v144
	v_fmac_f32_e32 v111, v142, v142
	v_fmac_f32_e32 v78, v134, v134
	v_fmac_f32_e32 v79, v136, v136
	v_add_f32_e32 v154, v112, v113
	v_add_f32_e32 v110, v110, v111
	v_add_f32_e32 v78, v78, v79
	v_and_b32_e32 v111, 0xffff0000, v70
	v_and_b32_e32 v113, 0xffff0000, v71
	v_and_b32_e32 v151, 0xffff0000, v68
	v_and_b32_e32 v149, 0xffff0000, v69
	v_add_f32_e32 v78, v110, v78
	v_lshlrev_b32_e32 v110, 16, v70
	v_lshlrev_b32_e32 v112, 16, v71
	v_mul_f32_e32 v70, v111, v111
	v_mul_f32_e32 v71, v113, v113
	v_lshlrev_b32_e32 v150, 16, v68
	v_lshlrev_b32_e32 v148, 16, v69
	v_mul_f32_e32 v68, v151, v151
	v_mul_f32_e32 v69, v149, v149
	v_fmac_f32_e32 v70, v110, v110
	v_fmac_f32_e32 v71, v112, v112
	v_fmac_f32_e32 v68, v150, v150
	v_fmac_f32_e32 v69, v148, v148
	s_waitcnt vmcnt(5)
	v_and_b32_e32 v139, 0xffff0000, v118
	v_and_b32_e32 v141, 0xffff0000, v119
	v_add_f32_e32 v70, v70, v71
	v_add_f32_e32 v68, v68, v69
	v_lshlrev_b32_e32 v138, 16, v118
	v_lshlrev_b32_e32 v140, 16, v119
	v_mul_f32_e32 v69, v139, v139
	v_mul_f32_e32 v71, v141, v141
	v_fmac_f32_e32 v69, v138, v138
	v_fmac_f32_e32 v71, v140, v140
	v_add_f32_e32 v69, v69, v71
	s_waitcnt vmcnt(3)
	v_lshlrev_b32_e32 v130, 16, v132
	v_and_b32_e32 v131, 0xffff0000, v132
	v_lshlrev_b32_e32 v132, 16, v133
	v_and_b32_e32 v133, 0xffff0000, v133
	v_add_f32_e32 v68, v68, v69
	v_mul_f32_e32 v69, v131, v131
	v_mul_f32_e32 v71, v133, v133
	v_fmac_f32_e32 v69, v130, v130
	v_fmac_f32_e32 v71, v132, v132
	v_add_f32_e32 v69, v69, v71
	s_waitcnt vmcnt(1)
	v_lshlrev_b32_e32 v118, 16, v120
	v_and_b32_e32 v119, 0xffff0000, v120
	v_lshlrev_b32_e32 v120, 16, v121
	v_and_b32_e32 v121, 0xffff0000, v121
	v_add_f32_e32 v68, v68, v69
	v_mul_f32_e32 v69, v119, v119
	v_mul_f32_e32 v71, v121, v121
	v_fmac_f32_e32 v69, v118, v118
	v_fmac_f32_e32 v71, v120, v120
	v_add_f32_e32 v69, v69, v71
	v_add_f32_e32 v68, v68, v69
	ds_bpermute_b32 v69, v97, v152
	v_and_b32_e32 v123, 0xffff0000, v76
	v_and_b32_e32 v125, 0xffff0000, v77
	v_lshlrev_b32_e32 v122, 16, v76
	v_lshlrev_b32_e32 v124, 16, v77
	s_waitcnt lgkmcnt(0)
	v_add_f32_e32 v69, v152, v69
	ds_bpermute_b32 v71, v147, v69
	v_mul_f32_e32 v76, v123, v123
	v_mul_f32_e32 v77, v125, v125
	v_fmac_f32_e32 v76, v122, v122
	v_fmac_f32_e32 v77, v124, v124
	s_waitcnt lgkmcnt(0)
	v_add_f32_e32 v69, v69, v71
	ds_bpermute_b32 v71, v153, v69
	v_add_f32_e32 v76, v76, v77
	v_add_f32_e32 v76, v78, v76
	v_add_f32_e32 v70, v76, v70
	s_waitcnt lgkmcnt(0)
	v_add_f32_e32 v69, v69, v71
	ds_bpermute_b32 v71, v155, v69
	s_waitcnt lgkmcnt(0)
	v_add_f32_e32 v69, v69, v71
	ds_bpermute_b32 v71, v157, v69
	s_waitcnt lgkmcnt(0)
	v_add_f32_e32 v69, v69, v71
	ds_bpermute_b32 v71, v159, v69
	s_waitcnt lgkmcnt(0)
	v_add_f32_e32 v69, v69, v71
	v_fmamk_f32 v69, v69, 0x3a800000, v177
	v_cmp_gt_f32_e32 vcc, s53, v69
	v_mul_f32_e32 v71, 0x4f800000, v69
	s_nop 0
	v_cndmask_b32_e32 v69, v69, v71, vcc
	v_sqrt_f32_e32 v71, v69
	s_nop 0
	v_add_u32_e32 v76, -1, v71
	v_fma_f32 v77, -v76, v71, v69
	v_cmp_ge_f32_e64 s[4:5], 0, v77
	v_add_u32_e32 v77, 1, v71
	s_nop 0
	v_cndmask_b32_e64 v76, v71, v76, s[4:5]
	v_fma_f32 v71, -v77, v71, v69
	v_cmp_lt_f32_e64 s[4:5], 0, v71
	s_nop 1
	v_cndmask_b32_e64 v71, v76, v77, s[4:5]
	v_mul_f32_e32 v76, 0x37800000, v71
	v_cndmask_b32_e32 v71, v71, v76, vcc
	v_cmp_class_f32_e32 vcc, v69, v234
	s_nop 1
	v_cndmask_b32_e32 v69, v71, v69, vcc
	v_div_scale_f32 v71, s[2:3], v69, v69, 1.0
	v_rcp_f32_e32 v76, v71
	s_nop 0
	v_fma_f32 v77, -v71, v76, 1.0
	v_fmac_f32_e32 v76, v77, v76
	v_div_scale_f32 v77, vcc, 1.0, v69, 1.0
	v_mul_f32_e32 v78, v77, v76
	v_fma_f32 v79, -v71, v78, v77
	v_fmac_f32_e32 v78, v79, v76
	v_fma_f32 v71, -v71, v78, v77
	v_div_fmas_f32 v71, v71, v76, v78
	v_div_fixup_f32 v152, v71, v69, 1.0
	ds_bpermute_b32 v69, v97, v154
	v_pk_mul_f32 v[62:63], v[152:153], v[62:63] op_sel_hi:[0,1]
	v_pk_mul_f32 v[60:61], v[152:153], v[60:61] op_sel_hi:[0,1]
	s_waitcnt lgkmcnt(0)
	v_add_f32_e32 v69, v154, v69
	ds_bpermute_b32 v71, v147, v69
	s_waitcnt lgkmcnt(0)
	v_add_f32_e32 v69, v69, v71
	ds_bpermute_b32 v71, v153, v69
	s_waitcnt lgkmcnt(0)
	v_add_f32_e32 v69, v69, v71
	ds_bpermute_b32 v71, v155, v69
	s_waitcnt lgkmcnt(0)
	v_add_f32_e32 v69, v69, v71
	ds_bpermute_b32 v71, v157, v69
	s_waitcnt lgkmcnt(0)
	v_add_f32_e32 v69, v69, v71
	ds_bpermute_b32 v71, v159, v69
	s_waitcnt lgkmcnt(0)
	v_add_f32_e32 v69, v69, v71
	v_fmamk_f32 v69, v69, 0x3a800000, v177
	v_cmp_gt_f32_e32 vcc, s53, v69
	v_mul_f32_e32 v71, 0x4f800000, v69
	s_nop 0
	v_cndmask_b32_e32 v69, v69, v71, vcc
	v_sqrt_f32_e32 v71, v69
	s_nop 0
	v_add_u32_e32 v76, -1, v71
	v_fma_f32 v77, -v76, v71, v69
	v_cmp_ge_f32_e64 s[4:5], 0, v77
	v_add_u32_e32 v77, 1, v71
	s_nop 0
	v_cndmask_b32_e64 v76, v71, v76, s[4:5]
	v_fma_f32 v71, -v77, v71, v69
	v_cmp_lt_f32_e64 s[4:5], 0, v71
	s_nop 1
	v_cndmask_b32_e64 v71, v76, v77, s[4:5]
	v_mul_f32_e32 v76, 0x37800000, v71
	v_cndmask_b32_e32 v71, v71, v76, vcc
	v_cmp_class_f32_e32 vcc, v69, v234
	s_nop 1
	v_cndmask_b32_e32 v69, v71, v69, vcc
	v_div_scale_f32 v71, s[2:3], v69, v69, 1.0
	v_rcp_f32_e32 v76, v71
	s_nop 0
	v_fma_f32 v77, -v71, v76, 1.0
	v_fmac_f32_e32 v76, v77, v76
	v_div_scale_f32 v77, vcc, 1.0, v69, 1.0
	v_mul_f32_e32 v78, v77, v76
	v_fma_f32 v79, -v71, v78, v77
	v_fmac_f32_e32 v78, v79, v76
	v_fma_f32 v71, -v71, v78, v77
	v_div_fmas_f32 v71, v71, v76, v78
	v_div_fixup_f32 v154, v71, v69, 1.0
	ds_bpermute_b32 v69, v97, v70
	s_waitcnt lgkmcnt(0)
	v_add_f32_e32 v69, v70, v69
	ds_bpermute_b32 v70, v147, v69
	s_waitcnt lgkmcnt(0)
	v_add_f32_e32 v69, v69, v70
	ds_bpermute_b32 v70, v153, v69
	s_waitcnt lgkmcnt(0)
	v_add_f32_e32 v69, v69, v70
	ds_bpermute_b32 v70, v155, v69
	s_waitcnt lgkmcnt(0)
	v_add_f32_e32 v69, v69, v70
	ds_bpermute_b32 v70, v157, v69
	s_waitcnt lgkmcnt(0)
	v_add_f32_e32 v69, v69, v70
	ds_bpermute_b32 v70, v159, v69
	s_waitcnt lgkmcnt(0)
	v_add_f32_e32 v69, v69, v70
	v_fmamk_f32 v69, v69, 0x3a800000, v177
	v_cmp_gt_f32_e32 vcc, s53, v69
	v_mul_f32_e32 v70, 0x4f800000, v69
	s_nop 0
	v_cndmask_b32_e32 v69, v69, v70, vcc
	v_sqrt_f32_e32 v70, v69
	s_nop 0
	v_add_u32_e32 v71, -1, v70
	v_fma_f32 v76, -v71, v70, v69
	v_cmp_ge_f32_e64 s[4:5], 0, v76
	v_add_u32_e32 v76, 1, v70
	s_nop 0
	v_cndmask_b32_e64 v71, v70, v71, s[4:5]
	v_fma_f32 v70, -v76, v70, v69
	v_cmp_lt_f32_e64 s[4:5], 0, v70
	s_nop 1
	v_cndmask_b32_e64 v70, v71, v76, s[4:5]
	v_mul_f32_e32 v71, 0x37800000, v70
	v_cndmask_b32_e32 v70, v70, v71, vcc
	v_cmp_class_f32_e32 vcc, v69, v234
	s_nop 1
	v_cndmask_b32_e32 v69, v70, v69, vcc
	v_div_scale_f32 v70, s[2:3], v69, v69, 1.0
	v_rcp_f32_e32 v71, v70
	s_nop 0
	v_fma_f32 v76, -v70, v71, 1.0
	v_fmac_f32_e32 v71, v76, v71
	v_div_scale_f32 v76, vcc, 1.0, v69, 1.0
	v_mul_f32_e32 v77, v76, v71
	v_fma_f32 v78, -v70, v77, v76
	v_fmac_f32_e32 v77, v78, v71
	v_fma_f32 v70, -v70, v77, v76
	v_div_fmas_f32 v70, v70, v71, v77
	v_div_fixup_f32 v156, v70, v69, 1.0
	ds_bpermute_b32 v69, v97, v68
	s_waitcnt lgkmcnt(0)
	v_add_f32_e32 v68, v68, v69
	ds_bpermute_b32 v69, v147, v68
	s_waitcnt lgkmcnt(0)
	v_add_f32_e32 v68, v68, v69
	ds_bpermute_b32 v69, v153, v68
	s_waitcnt lgkmcnt(0)
	v_add_f32_e32 v68, v68, v69
	ds_bpermute_b32 v69, v155, v68
	s_waitcnt lgkmcnt(0)
	v_add_f32_e32 v68, v68, v69
	ds_bpermute_b32 v69, v157, v68
	s_waitcnt lgkmcnt(0)
	v_add_f32_e32 v68, v68, v69
	ds_bpermute_b32 v69, v159, v68
	s_waitcnt lgkmcnt(0)
	v_add_f32_e32 v68, v68, v69
	v_fmamk_f32 v68, v68, 0x3a800000, v177
	v_cmp_gt_f32_e32 vcc, s53, v68
	v_mul_f32_e32 v69, 0x4f800000, v68
	s_nop 0
	v_cndmask_b32_e32 v68, v68, v69, vcc
	v_sqrt_f32_e32 v69, v68
	s_nop 0
	v_add_u32_e32 v70, -1, v69
	v_fma_f32 v71, -v70, v69, v68
	v_cmp_ge_f32_e64 s[4:5], 0, v71
	v_add_u32_e32 v71, 1, v69
	s_nop 0
	v_cndmask_b32_e64 v70, v69, v70, s[4:5]
	v_fma_f32 v69, -v71, v69, v68
	v_cmp_lt_f32_e64 s[4:5], 0, v69
	s_nop 1
	v_cndmask_b32_e64 v69, v70, v71, s[4:5]
	v_mul_f32_e32 v70, 0x37800000, v69
	v_cndmask_b32_e32 v69, v69, v70, vcc
	v_cmp_class_f32_e32 vcc, v68, v234
	s_nop 1
	v_cndmask_b32_e32 v68, v69, v68, vcc
	v_div_scale_f32 v69, s[2:3], v68, v68, 1.0
	v_rcp_f32_e32 v70, v69
	s_nop 0
	v_fma_f32 v71, -v69, v70, 1.0
	v_fmac_f32_e32 v70, v71, v70
	v_div_scale_f32 v71, vcc, 1.0, v68, 1.0
	v_mul_f32_e32 v76, v71, v70
	v_fma_f32 v77, -v69, v76, v71
	v_fmac_f32_e32 v76, v77, v70
	v_fma_f32 v69, -v69, v76, v71
	v_div_fmas_f32 v69, v69, v70, v76
	global_load_dwordx4 v[76:79], v[84:85], off
	v_add_co_u32_e32 v162, vcc, s79, v160
	v_div_fixup_f32 v158, v69, v68, 1.0
	s_nop 0
	v_addc_co_u32_e32 v163, vcc, 0, v161, vcc
	v_add_co_u32_e32 v164, vcc, s21, v160
	s_waitcnt vmcnt(0)
	v_pk_fma_f32 v[70:71], v[60:61], v[78:79], v[42:43]
	v_pk_fma_f32 v[68:69], v[62:63], v[76:77], v[40:41]
	v_pk_mul_f32 v[40:41], v[154:155], v[74:75] op_sel_hi:[0,1]
	v_pk_mul_f32 v[42:43], v[154:155], v[72:73] op_sel_hi:[0,1]
	v_pk_fma_f32 v[62:63], v[42:43], v[78:79], v[50:51]
	v_pk_fma_f32 v[60:61], v[40:41], v[76:77], v[48:49]
	v_addc_co_u32_e32 v165, vcc, 0, v161, vcc
	v_pk_mul_f32 v[40:41], v[156:157], v[144:145] op_sel_hi:[0,1]
	v_pk_mul_f32 v[42:43], v[156:157], v[142:143] op_sel_hi:[0,1]
	v_pk_fma_f32 v[74:75], v[78:79], v[42:43], v[54:55]
	v_pk_fma_f32 v[72:73], v[76:77], v[40:41], v[52:53]
	v_pk_mul_f32 v[40:41], v[158:159], v[150:151] op_sel_hi:[0,1]
	v_pk_mul_f32 v[42:43], v[158:159], v[148:149] op_sel_hi:[0,1]
	v_add_co_u32_e32 v142, vcc, s22, v160
	v_pk_fma_f32 v[54:55], v[78:79], v[42:43], v[66:67]
	v_pk_fma_f32 v[52:53], v[76:77], v[40:41], v[64:65]
	v_addc_co_u32_e32 v143, vcc, 0, v161, vcc
	global_store_dwordx4 v[160:161], v[68:71], off sc1
	global_store_dwordx4 v[164:165], v[60:63], off offset:-4096 sc1
	global_store_dwordx4 v[164:165], v[72:75], off sc1
	global_store_dwordx4 v[142:143], v[52:55], off sc1
	global_load_dwordx4 v[76:79], v[84:85], off offset:1024
	v_pk_mul_f32 v[40:41], v[152:153], v[104:105] op_sel_hi:[0,1]
	v_pk_mul_f32 v[42:43], v[152:153], v[102:103] op_sel_hi:[0,1]
	s_andn2_b64 vcc, exec, s[14:15]
	s_waitcnt vmcnt(0)
	v_pk_fma_f32 v[64:65], v[42:43], v[76:77], v[24:25]
	v_pk_fma_f32 v[66:67], v[40:41], v[78:79], v[26:27]
	v_pk_mul_f32 v[24:25], v[154:155], v[128:129] op_sel_hi:[0,1]
	v_pk_mul_f32 v[26:27], v[154:155], v[126:127] op_sel_hi:[0,1]
	v_pk_fma_f32 v[48:49], v[26:27], v[76:77], v[32:33]
	v_pk_fma_f32 v[50:51], v[24:25], v[78:79], v[34:35]
	v_pk_mul_f32 v[24:25], v[156:157], v[136:137] op_sel_hi:[0,1]
	v_pk_mul_f32 v[26:27], v[156:157], v[134:135] op_sel_hi:[0,1]
	v_pk_fma_f32 v[40:41], v[26:27], v[76:77], v[36:37]
	v_pk_fma_f32 v[42:43], v[24:25], v[78:79], v[38:39]
	v_pk_mul_f32 v[24:25], v[158:159], v[140:141] op_sel_hi:[0,1]
	v_pk_mul_f32 v[26:27], v[158:159], v[138:139] op_sel_hi:[0,1]
	v_pk_fma_f32 v[36:37], v[76:77], v[26:27], v[56:57]
	v_pk_fma_f32 v[38:39], v[78:79], v[24:25], v[58:59]
	global_store_dwordx4 v[160:161], v[64:67], off offset:1024 sc1
	global_store_dwordx4 v[162:163], v[48:51], off offset:1024 sc1
	global_store_dwordx4 v[164:165], v[40:43], off offset:1024 sc1
	global_store_dwordx4 v[142:143], v[36:39], off offset:1024 sc1
	global_load_dwordx4 v[56:59], v[84:85], off offset:2048
	v_pk_mul_f32 v[24:25], v[152:153], v[100:101] op_sel_hi:[0,1]
	v_pk_mul_f32 v[26:27], v[152:153], v[98:99] op_sel_hi:[0,1]
	s_waitcnt vmcnt(0)
	v_pk_fma_f32 v[32:33], v[26:27], v[56:57], v[12:13]
	v_pk_fma_f32 v[34:35], v[24:25], v[58:59], v[14:15]
	v_pk_mul_f32 v[12:13], v[154:155], v[116:117] op_sel_hi:[0,1]
	v_pk_mul_f32 v[14:15], v[154:155], v[114:115] op_sel_hi:[0,1]
	v_pk_fma_f32 v[24:25], v[14:15], v[56:57], v[16:17]
	v_pk_fma_f32 v[26:27], v[12:13], v[58:59], v[18:19]
	v_pk_mul_f32 v[12:13], v[156:157], v[124:125] op_sel_hi:[0,1]
	v_pk_mul_f32 v[14:15], v[156:157], v[122:123] op_sel_hi:[0,1]
	v_pk_fma_f32 v[20:21], v[14:15], v[56:57], v[20:21]
	v_pk_fma_f32 v[22:23], v[12:13], v[58:59], v[22:23]
	v_pk_mul_f32 v[12:13], v[158:159], v[132:133] op_sel_hi:[0,1]
	v_pk_mul_f32 v[14:15], v[158:159], v[130:131] op_sel_hi:[0,1]
	v_pk_fma_f32 v[16:17], v[14:15], v[56:57], v[44:45]
	v_pk_fma_f32 v[18:19], v[12:13], v[58:59], v[46:47]
	global_store_dwordx4 v[160:161], v[32:35], off offset:2048 sc1
	global_store_dwordx4 v[162:163], v[24:27], off offset:2048 sc1
	global_store_dwordx4 v[164:165], v[20:23], off offset:2048 sc1
	global_store_dwordx4 v[142:143], v[16:19], off offset:2048 sc1
	global_load_dwordx4 v[44:47], v[84:85], off offset:3072
	v_pk_mul_f32 v[14:15], v[152:153], v[94:95] op_sel_hi:[0,1]
	v_pk_mul_f32 v[12:13], v[152:153], v[92:93] op_sel_hi:[0,1]
	s_waitcnt vmcnt(0)
	v_pk_fma_f32 v[12:13], v[12:13], v[44:45], v[0:1]
	v_pk_fma_f32 v[14:15], v[14:15], v[46:47], v[2:3]
	v_pk_mul_f32 v[0:1], v[154:155], v[108:109] op_sel_hi:[0,1]
	v_pk_mul_f32 v[2:3], v[154:155], v[106:107] op_sel_hi:[0,1]
	v_pk_fma_f32 v[8:9], v[2:3], v[44:45], v[8:9]
	v_pk_fma_f32 v[10:11], v[0:1], v[46:47], v[10:11]
	v_pk_mul_f32 v[0:1], v[156:157], v[112:113] op_sel_hi:[0,1]
	v_pk_mul_f32 v[2:3], v[156:157], v[110:111] op_sel_hi:[0,1]
	v_pk_fma_f32 v[4:5], v[2:3], v[44:45], v[4:5]
	v_pk_fma_f32 v[6:7], v[0:1], v[46:47], v[6:7]
	v_pk_mul_f32 v[2:3], v[158:159], v[120:121] op_sel_hi:[0,1]
	v_pk_mul_f32 v[0:1], v[158:159], v[118:119] op_sel_hi:[0,1]
	v_pk_fma_f32 v[0:1], v[0:1], v[44:45], v[28:29]
	v_pk_fma_f32 v[2:3], v[2:3], v[46:47], v[30:31]
	global_store_dwordx4 v[160:161], v[12:15], off offset:3072 sc1
	global_store_dwordx4 v[162:163], v[8:11], off offset:3072 sc1
	global_store_dwordx4 v[164:165], v[4:7], off offset:3072 sc1
	global_store_dwordx4 v[142:143], v[0:3], off offset:3072 sc1
	s_cbranch_vccnz .LBB0_1437
	v_mul_f32_e32 v28, v53, v53
	v_mul_f32_e32 v29, v55, v55
	v_fmac_f32_e32 v28, v52, v52
	v_fmac_f32_e32 v29, v54, v54
	v_add_f32_e32 v28, v28, v29
	v_mul_f32_e32 v29, v37, v37
	v_mul_f32_e32 v30, v39, v39
	v_fmac_f32_e32 v29, v36, v36
	v_fmac_f32_e32 v30, v38, v38
	v_add_f32_e32 v29, v29, v30
	v_add_f32_e32 v28, v28, v29
	v_mul_f32_e32 v29, v17, v17
	v_mul_f32_e32 v30, v19, v19
	v_fmac_f32_e32 v29, v16, v16
	v_fmac_f32_e32 v30, v18, v18
	v_add_f32_e32 v29, v29, v30
	v_add_f32_e32 v28, v28, v29
	v_mul_f32_e32 v29, v1, v1
	v_mul_f32_e32 v30, v3, v3
	v_fmac_f32_e32 v29, v0, v0
	v_fmac_f32_e32 v30, v2, v2
	v_add_f32_e32 v29, v29, v30
	v_add_f32_e32 v28, v28, v29
	v_mul_f32_e32 v29, v73, v73
	v_mul_f32_e32 v30, v75, v75
	v_fmac_f32_e32 v29, v72, v72
	v_fmac_f32_e32 v30, v74, v74
	v_add_f32_e32 v29, v29, v30
	v_mul_f32_e32 v30, v41, v41
	v_mul_f32_e32 v31, v43, v43
	v_fmac_f32_e32 v30, v40, v40
	v_fmac_f32_e32 v31, v42, v42
	v_add_f32_e32 v30, v30, v31
	v_add_f32_e32 v29, v29, v30
	v_mul_f32_e32 v30, v21, v21
	v_mul_f32_e32 v31, v23, v23
	v_fmac_f32_e32 v30, v20, v20
	v_fmac_f32_e32 v31, v22, v22
	v_add_f32_e32 v30, v30, v31
	v_add_f32_e32 v29, v29, v30
	v_mul_f32_e32 v30, v5, v5
	v_mul_f32_e32 v31, v7, v7
	v_fmac_f32_e32 v30, v4, v4
	v_fmac_f32_e32 v31, v6, v6
	v_add_f32_e32 v30, v30, v31
	v_add_f32_e32 v29, v29, v30
	v_mul_f32_e32 v30, v61, v61
	v_mul_f32_e32 v31, v63, v63
	v_fmac_f32_e32 v30, v60, v60
	v_fmac_f32_e32 v31, v62, v62
	v_add_f32_e32 v30, v30, v31
	v_mul_f32_e32 v31, v49, v49
	v_mul_f32_e32 v44, v51, v51
	v_fmac_f32_e32 v31, v48, v48
	v_fmac_f32_e32 v44, v50, v50
	v_add_f32_e32 v31, v31, v44
	v_add_f32_e32 v30, v30, v31
	v_mul_f32_e32 v31, v25, v25
	v_mul_f32_e32 v44, v27, v27
	v_fmac_f32_e32 v31, v24, v24
	v_fmac_f32_e32 v44, v26, v26
	v_add_f32_e32 v31, v31, v44
	v_add_f32_e32 v30, v30, v31
	v_mul_f32_e32 v31, v9, v9
	v_mul_f32_e32 v44, v11, v11
	v_fmac_f32_e32 v31, v8, v8
	v_fmac_f32_e32 v44, v10, v10
	v_add_f32_e32 v31, v31, v44
	v_add_f32_e32 v30, v30, v31
	v_mul_f32_e32 v31, v69, v69
	v_mul_f32_e32 v44, v71, v71
	v_fmac_f32_e32 v31, v68, v68
	v_fmac_f32_e32 v44, v70, v70
	v_add_f32_e32 v31, v31, v44
	v_mul_f32_e32 v44, v65, v65
	v_mul_f32_e32 v45, v67, v67
	v_fmac_f32_e32 v44, v64, v64
	v_fmac_f32_e32 v45, v66, v66
	v_add_f32_e32 v44, v44, v45
	v_add_f32_e32 v31, v31, v44
	v_mul_f32_e32 v44, v33, v33
	v_mul_f32_e32 v45, v35, v35
	v_fmac_f32_e32 v44, v32, v32
	v_fmac_f32_e32 v45, v34, v34
	v_add_f32_e32 v44, v44, v45
	v_add_f32_e32 v31, v31, v44
	v_mul_f32_e32 v44, v13, v13
	v_mul_f32_e32 v45, v15, v15
	v_fmac_f32_e32 v44, v12, v12
	v_fmac_f32_e32 v45, v14, v14
	v_add_f32_e32 v44, v44, v45
	v_add_f32_e32 v31, v31, v44
	ds_bpermute_b32 v44, v97, v31
	s_lshl_b64 s[18:19], s[16:17], 10
	s_waitcnt lgkmcnt(0)
	v_add_f32_e32 v31, v31, v44
	ds_bpermute_b32 v44, v147, v31
	s_waitcnt lgkmcnt(0)
	v_add_f32_e32 v31, v31, v44
	ds_bpermute_b32 v44, v153, v31
	s_waitcnt lgkmcnt(0)
	v_add_f32_e32 v31, v31, v44
	ds_bpermute_b32 v44, v155, v31
	s_waitcnt lgkmcnt(0)
	v_add_f32_e32 v31, v31, v44
	ds_bpermute_b32 v44, v157, v31
	s_waitcnt lgkmcnt(0)
	v_add_f32_e32 v31, v31, v44
	ds_bpermute_b32 v44, v159, v31
	s_waitcnt lgkmcnt(0)
	v_add_f32_e32 v31, v31, v44
	v_fmamk_f32 v31, v31, 0x3a800000, v177
	v_cmp_gt_f32_e32 vcc, s53, v31
	v_mul_f32_e32 v44, 0x4f800000, v31
	s_nop 0
	v_cndmask_b32_e32 v31, v31, v44, vcc
	v_sqrt_f32_e32 v44, v31
	s_nop 0
	v_add_u32_e32 v45, -1, v44
	v_fma_f32 v46, -v45, v44, v31
	v_cmp_ge_f32_e64 s[4:5], 0, v46
	v_add_u32_e32 v46, 1, v44
	s_nop 0
	v_cndmask_b32_e64 v45, v44, v45, s[4:5]
	v_fma_f32 v44, -v46, v44, v31
	v_cmp_lt_f32_e64 s[4:5], 0, v44
	s_nop 1
	v_cndmask_b32_e64 v44, v45, v46, s[4:5]
	v_mul_f32_e32 v45, 0x37800000, v44
	v_cndmask_b32_e32 v44, v44, v45, vcc
	v_cmp_class_f32_e32 vcc, v31, v234
	s_nop 1
	v_cndmask_b32_e32 v31, v44, v31, vcc
	v_div_scale_f32 v44, s[2:3], v31, v31, 1.0
	v_rcp_f32_e32 v45, v44
	s_nop 0
	v_fma_f32 v46, -v44, v45, 1.0
	v_fmac_f32_e32 v45, v46, v45
	v_div_scale_f32 v46, vcc, 1.0, v31, 1.0
	v_mul_f32_e32 v47, v46, v45
	v_fma_f32 v56, -v44, v47, v46
	v_fmac_f32_e32 v47, v56, v45
	v_fma_f32 v44, -v44, v47, v46
	v_div_fmas_f32 v44, v44, v45, v47
	v_div_fixup_f32 v56, v44, v31, 1.0
	ds_bpermute_b32 v31, v97, v30
	v_mul_f32_e32 v32, v32, v56
	v_mul_f32_e32 v33, v33, v56
	v_mul_f32_e32 v12, v12, v56
	v_mul_f32_e32 v13, v13, v56
	s_waitcnt lgkmcnt(0)
	v_add_f32_e32 v30, v30, v31
	ds_bpermute_b32 v31, v147, v30
	s_waitcnt lgkmcnt(0)
	v_add_f32_e32 v30, v30, v31
	ds_bpermute_b32 v31, v153, v30
	s_waitcnt lgkmcnt(0)
	v_add_f32_e32 v30, v30, v31
	ds_bpermute_b32 v31, v155, v30
	s_waitcnt lgkmcnt(0)
	v_add_f32_e32 v30, v30, v31
	ds_bpermute_b32 v31, v157, v30
	s_waitcnt lgkmcnt(0)
	v_add_f32_e32 v30, v30, v31
	ds_bpermute_b32 v31, v159, v30
	s_waitcnt lgkmcnt(0)
	v_add_f32_e32 v30, v30, v31
	v_fmamk_f32 v30, v30, 0x3a800000, v177
	v_cmp_gt_f32_e32 vcc, s53, v30
	v_mul_f32_e32 v31, 0x4f800000, v30
	s_nop 0
	v_cndmask_b32_e32 v30, v30, v31, vcc
	v_sqrt_f32_e32 v31, v30
	s_nop 0
	v_add_u32_e32 v44, -1, v31
	v_fma_f32 v45, -v44, v31, v30
	v_cmp_ge_f32_e64 s[4:5], 0, v45
	v_add_u32_e32 v45, 1, v31
	s_nop 0
	v_cndmask_b32_e64 v44, v31, v44, s[4:5]
	v_fma_f32 v31, -v45, v31, v30
	v_cmp_lt_f32_e64 s[4:5], 0, v31
	s_nop 1
	v_cndmask_b32_e64 v31, v44, v45, s[4:5]
	v_mul_f32_e32 v44, 0x37800000, v31
	v_cndmask_b32_e32 v31, v31, v44, vcc
	v_cmp_class_f32_e32 vcc, v30, v234
	s_nop 1
	v_cndmask_b32_e32 v30, v31, v30, vcc
	v_div_scale_f32 v31, s[2:3], v30, v30, 1.0
	v_rcp_f32_e32 v44, v31
	s_nop 0
	v_fma_f32 v45, -v31, v44, 1.0
	v_fmac_f32_e32 v44, v45, v44
	v_div_scale_f32 v45, vcc, 1.0, v30, 1.0
	v_mul_f32_e32 v46, v45, v44
	v_fma_f32 v47, -v31, v46, v45
	v_fmac_f32_e32 v46, v47, v44
	v_fma_f32 v31, -v31, v46, v45
	v_div_fmas_f32 v31, v31, v44, v46
	v_div_fixup_f32 v57, v31, v30, 1.0
	ds_bpermute_b32 v30, v97, v29
	v_mul_f32_e32 v47, v69, v56
	v_mul_f32_e32 v48, v48, v57
	v_mul_f32_e32 v49, v49, v57
	v_mul_f32_e32 v24, v24, v57
	s_waitcnt lgkmcnt(0)
	v_add_f32_e32 v29, v29, v30
	ds_bpermute_b32 v30, v147, v29
	v_mul_f32_e32 v25, v25, v57
	v_mul_f32_e32 v8, v8, v57
	v_mul_f32_e32 v9, v9, v57
	s_waitcnt lgkmcnt(0)
	v_add_f32_e32 v29, v29, v30
	ds_bpermute_b32 v30, v153, v29
	s_waitcnt lgkmcnt(0)
	v_add_f32_e32 v29, v29, v30
	ds_bpermute_b32 v30, v155, v29
	s_waitcnt lgkmcnt(0)
	v_add_f32_e32 v29, v29, v30
	ds_bpermute_b32 v30, v157, v29
	s_waitcnt lgkmcnt(0)
	v_add_f32_e32 v29, v29, v30
	ds_bpermute_b32 v30, v159, v29
	s_waitcnt lgkmcnt(0)
	v_add_f32_e32 v29, v29, v30
	v_fmamk_f32 v29, v29, 0x3a800000, v177
	v_cmp_gt_f32_e32 vcc, s53, v29
	v_mul_f32_e32 v30, 0x4f800000, v29
	s_nop 0
	v_cndmask_b32_e32 v29, v29, v30, vcc
	v_sqrt_f32_e32 v30, v29
	s_nop 0
	v_add_u32_e32 v31, -1, v30
	v_fma_f32 v44, -v31, v30, v29
	v_cmp_ge_f32_e64 s[4:5], 0, v44
	v_add_u32_e32 v44, 1, v30
	s_nop 0
	v_cndmask_b32_e64 v31, v30, v31, s[4:5]
	v_fma_f32 v30, -v44, v30, v29
	v_cmp_lt_f32_e64 s[4:5], 0, v30
	s_nop 1
	v_cndmask_b32_e64 v30, v31, v44, s[4:5]
	v_mul_f32_e32 v31, 0x37800000, v30
	v_cndmask_b32_e32 v30, v30, v31, vcc
	v_cmp_class_f32_e32 vcc, v29, v234
	s_nop 1
	v_cndmask_b32_e32 v29, v30, v29, vcc
	v_div_scale_f32 v30, s[2:3], v29, v29, 1.0
	v_rcp_f32_e32 v31, v30
	s_nop 0
	v_fma_f32 v44, -v30, v31, 1.0
	v_fmac_f32_e32 v31, v44, v31
	v_div_scale_f32 v44, vcc, 1.0, v29, 1.0
	v_mul_f32_e32 v45, v44, v31
	v_fma_f32 v46, -v30, v45, v44
	v_fmac_f32_e32 v45, v46, v31
	v_fma_f32 v30, -v30, v45, v44
	v_div_fmas_f32 v30, v30, v31, v45
	v_div_fixup_f32 v58, v30, v29, 1.0
	ds_bpermute_b32 v29, v97, v28
	v_mul_f32_e32 v46, v68, v56
	v_mul_f32_e32 v40, v40, v58
	v_mul_f32_e32 v41, v41, v58
	v_mul_f32_e32 v20, v20, v58
	s_waitcnt lgkmcnt(0)
	v_add_f32_e32 v28, v28, v29
	ds_bpermute_b32 v29, v147, v28
	v_mul_f32_e32 v21, v21, v58
	v_mul_f32_e32 v4, v4, v58
	v_mul_f32_e32 v5, v5, v58
	s_waitcnt lgkmcnt(0)
	v_add_f32_e32 v28, v28, v29
	ds_bpermute_b32 v29, v153, v28
	s_waitcnt lgkmcnt(0)
	v_add_f32_e32 v28, v28, v29
	ds_bpermute_b32 v29, v155, v28
	s_waitcnt lgkmcnt(0)
	v_add_f32_e32 v28, v28, v29
	ds_bpermute_b32 v29, v157, v28
	s_waitcnt lgkmcnt(0)
	v_add_f32_e32 v28, v28, v29
	ds_bpermute_b32 v29, v159, v28
	s_waitcnt lgkmcnt(0)
	v_add_f32_e32 v28, v28, v29
	v_fmamk_f32 v28, v28, 0x3a800000, v177
	v_cmp_gt_f32_e32 vcc, s53, v28
	v_mul_f32_e32 v29, 0x4f800000, v28
	s_nop 0
	v_cndmask_b32_e32 v28, v28, v29, vcc
	v_sqrt_f32_e32 v29, v28
	s_nop 0
	v_add_u32_e32 v30, -1, v29
	v_fma_f32 v31, -v30, v29, v28
	v_cmp_ge_f32_e64 s[4:5], 0, v31
	v_add_u32_e32 v31, 1, v29
	s_nop 0
	v_cndmask_b32_e64 v30, v29, v30, s[4:5]
	v_fma_f32 v29, -v31, v29, v28
	v_cmp_lt_f32_e64 s[4:5], 0, v29
	s_nop 1
	v_cndmask_b32_e64 v29, v30, v31, s[4:5]
	v_mul_f32_e32 v30, 0x37800000, v29
	v_cndmask_b32_e32 v29, v29, v30, vcc
	v_cmp_class_f32_e32 vcc, v28, v234
	s_nop 1
	v_cndmask_b32_e32 v28, v29, v28, vcc
	v_div_scale_f32 v29, s[2:3], v28, v28, 1.0
	v_rcp_f32_e32 v30, v29
	s_nop 0
	v_fma_f32 v31, -v29, v30, 1.0
	v_fmac_f32_e32 v30, v31, v30
	v_div_scale_f32 v31, vcc, 1.0, v28, 1.0
	v_mul_f32_e32 v44, v31, v30
	v_fma_f32 v45, -v29, v44, v31
	v_fmac_f32_e32 v44, v45, v30
	v_fma_f32 v29, -v29, v44, v31
	v_div_fmas_f32 v29, v29, v30, v44
	v_div_fixup_f32 v59, v29, v28, 1.0
	global_load_dwordx4 v[28:31], v[88:89], off
	v_lshl_add_u64 v[44:45], s[18:19], 1, v[90:91]
	v_mul_f32_e32 v52, v52, v59
	v_mul_f32_e32 v36, v36, v59
	v_mul_f32_e32 v16, v16, v59
	v_mul_f32_e32 v17, v17, v59
	v_mul_f32_e32 v0, v0, v59
	v_mul_f32_e32 v1, v1, v59
	s_waitcnt vmcnt(0)
	v_mul_f32_e32 v46, v46, v28
	v_mul_f32_e32 v47, v47, v29
	v_bfe_u32 v68, v46, 16, 1
	v_add3_u32 v46, v46, v68, s36
	v_bfe_u32 v68, v47, 16, 1
	v_lshrrev_b32_e32 v46, 16, v46
	v_add3_u32 v47, v47, v68, s36
	v_and_or_b32 v46, v47, s68, v46
	v_mul_f32_e32 v47, v70, v56
	v_mul_f32_e32 v47, v47, v30
	v_mul_f32_e32 v68, v71, v56
	v_mul_f32_e32 v68, v68, v31
	v_bfe_u32 v69, v47, 16, 1
	v_add3_u32 v47, v47, v69, s36
	v_bfe_u32 v69, v68, 16, 1
	v_lshrrev_b32_e32 v47, 16, v47
	v_add3_u32 v68, v68, v69, s36
	v_and_or_b32 v47, v68, s68, v47
	global_store_dwordx2 v[44:45], v[46:47], off sc1
	v_mul_f32_e32 v46, v60, v57
	v_mul_f32_e32 v46, v46, v28
	v_mul_f32_e32 v47, v61, v57
	v_mul_f32_e32 v47, v47, v29
	v_bfe_u32 v60, v46, 16, 1
	v_add3_u32 v46, v46, v60, s36
	v_bfe_u32 v60, v47, 16, 1
	v_lshrrev_b32_e32 v46, 16, v46
	v_add3_u32 v47, v47, v60, s36
	v_and_or_b32 v46, v47, s68, v46
	v_mul_f32_e32 v47, v62, v57
	v_mul_f32_e32 v47, v47, v30
	v_mul_f32_e32 v60, v63, v57
	v_mul_f32_e32 v60, v60, v31
	v_bfe_u32 v61, v47, 16, 1
	v_add3_u32 v47, v47, v61, s36
	v_bfe_u32 v61, v60, 16, 1
	v_lshrrev_b32_e32 v47, 16, v47
	v_add3_u32 v60, v60, v61, s36
	v_and_or_b32 v47, v60, s68, v47
	global_store_dwordx2 v[44:45], v[46:47], off offset:2048 sc1
	v_mul_f32_e32 v46, v72, v58
	v_mul_f32_e32 v46, v46, v28
	v_mul_f32_e32 v47, v73, v58
	v_mul_f32_e32 v47, v47, v29
	v_bfe_u32 v60, v46, 16, 1
	v_mul_f32_e32 v28, v28, v52
	v_mul_f32_e32 v52, v53, v59
	v_add3_u32 v46, v46, v60, s36
	v_bfe_u32 v60, v47, 16, 1
	v_mul_f32_e32 v29, v29, v52
	v_bfe_u32 v52, v28, 16, 1
	v_lshrrev_b32_e32 v46, 16, v46
	v_add3_u32 v47, v47, v60, s36
	v_add3_u32 v28, v28, v52, s36
	v_bfe_u32 v52, v29, 16, 1
	v_and_or_b32 v60, v47, s68, v46
	v_mul_f32_e32 v46, v74, v58
	v_lshrrev_b32_e32 v28, 16, v28
	v_add3_u32 v29, v29, v52, s36
	v_mul_f32_e32 v46, v46, v30
	v_mul_f32_e32 v47, v75, v58
	v_and_or_b32 v28, v29, s68, v28
	v_mul_f32_e32 v29, v54, v59
	v_mul_f32_e32 v47, v47, v31
	v_bfe_u32 v61, v46, 16, 1
	v_mul_f32_e32 v29, v30, v29
	v_mul_f32_e32 v30, v55, v59
	v_add3_u32 v46, v46, v61, s36
	v_bfe_u32 v61, v47, 16, 1
	v_mul_f32_e32 v30, v31, v30
	v_bfe_u32 v31, v29, 16, 1
	v_lshrrev_b32_e32 v46, 16, v46
	v_add3_u32 v47, v47, v61, s36
	v_add3_u32 v29, v29, v31, s36
	v_bfe_u32 v31, v30, 16, 1
	v_and_or_b32 v61, v47, s68, v46
	v_add_co_u32_e32 v46, vcc, s79, v44
	v_lshrrev_b32_e32 v29, 16, v29
	v_add3_u32 v30, v30, v31, s36
	v_addc_co_u32_e32 v47, vcc, 0, v45, vcc
	v_and_or_b32 v29, v30, s68, v29
	global_store_dwordx2 v[46:47], v[60:61], off sc1
	global_store_dwordx2 v[46:47], v[28:29], off offset:2048 sc1
	global_load_dwordx4 v[28:31], v[88:89], off offset:1024
	v_mul_f32_e32 v52, v64, v56
	v_mul_f32_e32 v53, v65, v56
	s_waitcnt vmcnt(0)
	v_mul_f32_e32 v52, v52, v28
	v_mul_f32_e32 v53, v53, v29
	v_bfe_u32 v54, v52, 16, 1
	v_add3_u32 v52, v52, v54, s36
	v_bfe_u32 v54, v53, 16, 1
	v_lshrrev_b32_e32 v52, 16, v52
	v_add3_u32 v53, v53, v54, s36
	v_and_or_b32 v52, v53, s68, v52
	v_mul_f32_e32 v53, v66, v56
	v_mul_f32_e32 v53, v53, v30
	v_mul_f32_e32 v54, v67, v56
	v_mul_f32_e32 v54, v54, v31
	v_bfe_u32 v55, v53, 16, 1
	v_add3_u32 v53, v53, v55, s36
	v_bfe_u32 v55, v54, 16, 1
	v_lshrrev_b32_e32 v53, 16, v53
	v_add3_u32 v54, v54, v55, s36
	v_and_or_b32 v53, v54, s68, v53
	v_mul_f32_e32 v48, v48, v28
	global_store_dwordx2 v[44:45], v[52:53], off offset:512 sc1
	v_mul_f32_e32 v49, v49, v29
	v_bfe_u32 v52, v48, 16, 1
	v_add3_u32 v48, v48, v52, s36
	v_bfe_u32 v52, v49, 16, 1
	v_lshrrev_b32_e32 v48, 16, v48
	v_add3_u32 v49, v49, v52, s36
	v_and_or_b32 v48, v49, s68, v48
	v_mul_f32_e32 v49, v50, v57
	v_mul_f32_e32 v49, v49, v30
	v_mul_f32_e32 v50, v51, v57
	v_mul_f32_e32 v50, v50, v31
	v_bfe_u32 v51, v49, 16, 1
	v_add3_u32 v49, v49, v51, s36
	v_bfe_u32 v51, v50, 16, 1
	v_lshrrev_b32_e32 v49, 16, v49
	v_add3_u32 v50, v50, v51, s36
	v_and_or_b32 v49, v50, s68, v49
	v_mul_f32_e32 v40, v40, v28
	v_mul_f32_e32 v28, v28, v36
	v_mul_f32_e32 v36, v37, v59
	global_store_dwordx2 v[44:45], v[48:49], off offset:2560 sc1
	v_mul_f32_e32 v41, v41, v29
	v_bfe_u32 v48, v40, 16, 1
	v_mul_f32_e32 v29, v29, v36
	v_bfe_u32 v36, v28, 16, 1
	v_add3_u32 v40, v40, v48, s36
	v_bfe_u32 v48, v41, 16, 1
	v_add3_u32 v28, v28, v36, s36
	v_bfe_u32 v36, v29, 16, 1
	v_lshrrev_b32_e32 v40, 16, v40
	v_add3_u32 v41, v41, v48, s36
	v_lshrrev_b32_e32 v28, 16, v28
	v_add3_u32 v29, v29, v36, s36
	v_and_or_b32 v40, v41, s68, v40
	v_mul_f32_e32 v41, v42, v58
	v_and_or_b32 v28, v29, s68, v28
	v_mul_f32_e32 v29, v38, v59
	v_mul_f32_e32 v41, v41, v30
	v_mul_f32_e32 v42, v43, v58
	v_mul_f32_e32 v29, v30, v29
	v_mul_f32_e32 v30, v39, v59
	v_mul_f32_e32 v42, v42, v31
	v_bfe_u32 v43, v41, 16, 1
	v_mul_f32_e32 v30, v31, v30
	v_bfe_u32 v31, v29, 16, 1
	v_add3_u32 v41, v41, v43, s36
	v_bfe_u32 v43, v42, 16, 1
	v_add3_u32 v29, v29, v31, s36
	v_bfe_u32 v31, v30, 16, 1
	v_lshrrev_b32_e32 v41, 16, v41
	v_add3_u32 v42, v42, v43, s36
	v_lshrrev_b32_e32 v29, 16, v29
	v_add3_u32 v30, v30, v31, s36
	v_and_or_b32 v41, v42, s68, v41
	v_and_or_b32 v29, v30, s68, v29
	global_store_dwordx2 v[46:47], v[40:41], off offset:512 sc1
	global_store_dwordx2 v[46:47], v[28:29], off offset:2560 sc1
	global_load_dwordx4 v[28:31], v[88:89], off offset:2048
	s_waitcnt vmcnt(0)
	v_mul_f32_e32 v32, v32, v28
	v_mul_f32_e32 v33, v33, v29
	v_bfe_u32 v36, v32, 16, 1
	v_add3_u32 v32, v32, v36, s36
	v_bfe_u32 v36, v33, 16, 1
	v_lshrrev_b32_e32 v32, 16, v32
	v_add3_u32 v33, v33, v36, s36
	v_and_or_b32 v32, v33, s68, v32
	v_mul_f32_e32 v33, v34, v56
	v_mul_f32_e32 v33, v33, v30
	v_mul_f32_e32 v34, v35, v56
	v_mul_f32_e32 v34, v34, v31
	v_bfe_u32 v35, v33, 16, 1
	v_add3_u32 v33, v33, v35, s36
	v_bfe_u32 v35, v34, 16, 1
	v_lshrrev_b32_e32 v33, 16, v33
	v_add3_u32 v34, v34, v35, s36
	v_and_or_b32 v33, v34, s68, v33
	v_mul_f32_e32 v24, v24, v28
	global_store_dwordx2 v[44:45], v[32:33], off offset:1024 sc1
	v_mul_f32_e32 v25, v25, v29
	v_bfe_u32 v32, v24, 16, 1
	v_add3_u32 v24, v24, v32, s36
	v_bfe_u32 v32, v25, 16, 1
	v_lshrrev_b32_e32 v24, 16, v24
	v_add3_u32 v25, v25, v32, s36
	v_and_or_b32 v24, v25, s68, v24
	v_mul_f32_e32 v25, v26, v57
	v_mul_f32_e32 v25, v25, v30
	v_mul_f32_e32 v26, v27, v57
	v_mul_f32_e32 v26, v26, v31
	v_bfe_u32 v27, v25, 16, 1
	v_add3_u32 v25, v25, v27, s36
	v_bfe_u32 v27, v26, 16, 1
	v_lshrrev_b32_e32 v25, 16, v25
	v_add3_u32 v26, v26, v27, s36
	v_and_or_b32 v25, v26, s68, v25
	v_mul_f32_e32 v20, v20, v28
	global_store_dwordx2 v[44:45], v[24:25], off offset:3072 sc1
	v_mul_f32_e32 v21, v21, v29
	v_bfe_u32 v24, v20, 16, 1
	v_add3_u32 v20, v20, v24, s36
	v_bfe_u32 v24, v21, 16, 1
	v_lshrrev_b32_e32 v20, 16, v20
	v_add3_u32 v21, v21, v24, s36
	v_and_or_b32 v20, v21, s68, v20
	v_mul_f32_e32 v21, v22, v58
	v_mul_f32_e32 v21, v21, v30
	v_mul_f32_e32 v22, v23, v58
	v_mul_f32_e32 v22, v22, v31
	v_bfe_u32 v23, v21, 16, 1
	v_add3_u32 v21, v21, v23, s36
	v_bfe_u32 v23, v22, 16, 1
	v_lshrrev_b32_e32 v21, 16, v21
	v_add3_u32 v22, v22, v23, s36
	v_and_or_b32 v21, v22, s68, v21
	v_mul_f32_e32 v16, v16, v28
	global_store_dwordx2 v[46:47], v[20:21], off offset:1024 sc1
	v_mul_f32_e32 v17, v17, v29
	v_bfe_u32 v20, v16, 16, 1
	v_add3_u32 v16, v16, v20, s36
	v_bfe_u32 v20, v17, 16, 1
	v_lshrrev_b32_e32 v16, 16, v16
	v_add3_u32 v17, v17, v20, s36
	v_and_or_b32 v16, v17, s68, v16
	v_mul_f32_e32 v17, v18, v59
	v_mul_f32_e32 v17, v17, v30
	v_mul_f32_e32 v18, v19, v59
	v_mul_f32_e32 v18, v18, v31
	v_bfe_u32 v19, v17, 16, 1
	v_add3_u32 v17, v17, v19, s36
	v_bfe_u32 v19, v18, 16, 1
	v_lshrrev_b32_e32 v17, 16, v17
	v_add3_u32 v18, v18, v19, s36
	v_and_or_b32 v17, v18, s68, v17
	global_store_dwordx2 v[46:47], v[16:17], off offset:3072 sc1
	global_load_dwordx4 v[16:19], v[88:89], off offset:3072
	s_waitcnt vmcnt(0)
	v_mul_f32_e32 v12, v12, v16
	v_mul_f32_e32 v13, v13, v17
	v_bfe_u32 v20, v12, 16, 1
	v_add3_u32 v12, v12, v20, s36
	v_bfe_u32 v20, v13, 16, 1
	v_lshrrev_b32_e32 v12, 16, v12
	v_add3_u32 v13, v13, v20, s36
	v_and_or_b32 v12, v13, s68, v12
	v_mul_f32_e32 v13, v14, v56
	v_mul_f32_e32 v13, v13, v18
	v_mul_f32_e32 v14, v15, v56
	v_mul_f32_e32 v14, v14, v19
	v_bfe_u32 v15, v13, 16, 1
	v_add3_u32 v13, v13, v15, s36
	v_bfe_u32 v15, v14, 16, 1
	v_lshrrev_b32_e32 v13, 16, v13
	v_add3_u32 v14, v14, v15, s36
	v_and_or_b32 v13, v14, s68, v13
	v_mul_f32_e32 v8, v8, v16
	global_store_dwordx2 v[44:45], v[12:13], off offset:1536 sc1
	v_mul_f32_e32 v9, v9, v17
	v_bfe_u32 v12, v8, 16, 1
	v_add3_u32 v8, v8, v12, s36
	v_bfe_u32 v12, v9, 16, 1
	v_lshrrev_b32_e32 v8, 16, v8
	v_add3_u32 v9, v9, v12, s36
	v_and_or_b32 v8, v9, s68, v8
	v_mul_f32_e32 v9, v10, v57
	v_mul_f32_e32 v9, v9, v18
	v_mul_f32_e32 v10, v11, v57
	v_mul_f32_e32 v10, v10, v19
	v_bfe_u32 v11, v9, 16, 1
	v_add3_u32 v9, v9, v11, s36
	v_bfe_u32 v11, v10, 16, 1
	v_lshrrev_b32_e32 v9, 16, v9
	v_add3_u32 v10, v10, v11, s36
	v_and_or_b32 v9, v10, s68, v9
	v_mul_f32_e32 v4, v4, v16
	global_store_dwordx2 v[44:45], v[8:9], off offset:3584 sc1
	v_mul_f32_e32 v5, v5, v17
	v_bfe_u32 v8, v4, 16, 1
	v_add3_u32 v4, v4, v8, s36
	v_bfe_u32 v8, v5, 16, 1
	v_lshrrev_b32_e32 v4, 16, v4
	v_add3_u32 v5, v5, v8, s36
	v_and_or_b32 v4, v5, s68, v4
	v_mul_f32_e32 v5, v6, v58
	v_mul_f32_e32 v5, v5, v18
	v_mul_f32_e32 v6, v7, v58
	v_mul_f32_e32 v6, v6, v19
	v_bfe_u32 v7, v5, 16, 1
	v_add3_u32 v5, v5, v7, s36
	v_bfe_u32 v7, v6, 16, 1
	v_lshrrev_b32_e32 v5, 16, v5
	v_add3_u32 v6, v6, v7, s36
	v_and_or_b32 v5, v6, s68, v5
	v_mul_f32_e32 v0, v0, v16
	global_store_dwordx2 v[46:47], v[4:5], off offset:1536 sc1
	v_mul_f32_e32 v1, v1, v17
	v_bfe_u32 v4, v0, 16, 1
	v_add3_u32 v0, v0, v4, s36
	v_bfe_u32 v4, v1, 16, 1
	v_lshrrev_b32_e32 v0, 16, v0
	v_add3_u32 v1, v1, v4, s36
	v_and_or_b32 v0, v1, s68, v0
	v_mul_f32_e32 v1, v2, v59
	v_mul_f32_e32 v1, v1, v18
	v_mul_f32_e32 v2, v3, v59
	v_mul_f32_e32 v2, v2, v19
	v_bfe_u32 v3, v1, 16, 1
	v_add3_u32 v1, v1, v3, s36
	v_bfe_u32 v3, v2, 16, 1
	v_lshrrev_b32_e32 v1, 16, v1
	v_add3_u32 v2, v2, v3, s36
	v_and_or_b32 v1, v2, s68, v1
	global_store_dwordx2 v[46:47], v[0:1], off offset:3584 sc1
	s_branch .LBB0_1437

.LBB0_1848:
	s_ashr_i32 s19, s18, 31
	s_lshl_b64 s[2:3], s[18:19], 11
	s_lshl_b64 s[20:21], s[18:19], 12
	v_lshl_add_u64 v[4:5], v[82:83], 0, s[2:3]
	v_lshl_add_u64 v[28:29], v[84:85], 0, s[20:21]
	global_load_dwordx2 v[64:65], v[4:5], off
	global_load_dwordx4 v[40:43], v[28:29], off
	global_load_dwordx2 v[94:95], v[4:5], off offset:512
	global_load_dwordx4 v[20:23], v[28:29], off offset:1024
	global_load_dwordx2 v[78:79], v[4:5], off offset:1024
	global_load_dwordx4 v[12:15], v[28:29], off offset:2048
	global_load_dwordx2 v[76:77], v[4:5], off offset:1536
	global_load_dwordx4 v[0:3], v[28:29], off offset:3072
	global_load_dwordx2 v[74:75], v[4:5], off offset:2048
	v_add_co_u32_e32 v6, vcc, s79, v28
	s_movk_i32 s23, 0x2000
	s_nop 0
	v_addc_co_u32_e32 v7, vcc, 0, v29, vcc
	v_add_co_u32_e32 v30, vcc, s23, v28
	s_movk_i32 s24, 0x3000
	s_nop 0
	v_addc_co_u32_e32 v31, vcc, 0, v29, vcc
	global_load_dwordx4 v[48:51], v[30:31], off offset:-4096
	global_load_dwordx2 v[108:109], v[4:5], off offset:2560
	global_load_dwordx4 v[32:35], v[6:7], off offset:1024
	global_load_dwordx2 v[118:119], v[4:5], off offset:3072
	global_load_dwordx4 v[16:19], v[6:7], off offset:2048
	global_load_dwordx2 v[110:111], v[4:5], off offset:3584
	global_load_dwordx4 v[8:11], v[6:7], off offset:3072
	v_add_co_u32_e32 v66, vcc, s79, v4
	v_lshl_add_u64 v[162:163], v[92:93], 0, s[20:21]
	s_nop 0
	v_addc_co_u32_e32 v67, vcc, 0, v5, vcc
	global_load_dwordx2 v[114:115], v[66:67], off
	global_load_dwordx4 v[52:55], v[30:31], off
	global_load_dwordx2 v[112:113], v[66:67], off offset:512
	global_load_dwordx4 v[36:39], v[30:31], off offset:1024
	global_load_dwordx2 v[72:73], v[66:67], off offset:1024
	global_load_dwordx4 v[24:27], v[30:31], off offset:2048
	global_load_dwordx2 v[70:71], v[66:67], off offset:1536
	global_load_dwordx4 v[4:7], v[30:31], off offset:3072
	global_load_dwordx2 v[68:69], v[66:67], off offset:2048
	v_add_co_u32_e32 v28, vcc, s24, v28
	s_waitcnt vmcnt(0)
	v_and_b32_e32 v105, 0xffff0000, v94
	v_addc_co_u32_e32 v29, vcc, 0, v29, vcc
	global_load_dwordx4 v[60:63], v[28:29], off
	global_load_dwordx2 v[132:133], v[66:67], off offset:2560
	global_load_dwordx4 v[56:59], v[28:29], off offset:1024
	global_load_dwordx2 v[120:121], v[66:67], off offset:3072
	global_load_dwordx4 v[44:47], v[28:29], off offset:2048
	global_load_dwordx2 v[122:123], v[66:67], off offset:3584
	s_nop 0
	global_load_dwordx4 v[28:31], v[28:29], off offset:3072
	v_lshlrev_b32_e32 v66, 16, v64
	v_and_b32_e32 v67, 0xffff0000, v64
	v_lshlrev_b32_e32 v64, 16, v65
	v_and_b32_e32 v65, 0xffff0000, v65
	v_and_b32_e32 v107, 0xffff0000, v95
	v_mul_f32_e32 v98, v67, v67
	v_mul_f32_e32 v99, v65, v65
	v_lshlrev_b32_e32 v104, 16, v94
	v_lshlrev_b32_e32 v106, 16, v95
	v_mul_f32_e32 v94, v105, v105
	v_mul_f32_e32 v95, v107, v107
	v_and_b32_e32 v101, 0xffff0000, v78
	v_and_b32_e32 v103, 0xffff0000, v79
	v_fmac_f32_e32 v98, v66, v66
	v_fmac_f32_e32 v99, v64, v64
	v_fmac_f32_e32 v94, v104, v104
	v_fmac_f32_e32 v95, v106, v106
	v_lshlrev_b32_e32 v100, 16, v78
	v_lshlrev_b32_e32 v102, 16, v79
	v_mul_f32_e32 v78, v101, v101
	v_mul_f32_e32 v79, v103, v103
	v_add_f32_e32 v98, v98, v99
	v_add_f32_e32 v94, v94, v95
	v_fmac_f32_e32 v78, v100, v100
	v_fmac_f32_e32 v79, v102, v102
	v_add_f32_e32 v94, v98, v94
	v_add_f32_e32 v78, v78, v79
	v_and_b32_e32 v95, 0xffff0000, v76
	v_and_b32_e32 v99, 0xffff0000, v77
	v_add_f32_e32 v78, v94, v78
	v_lshlrev_b32_e32 v94, 16, v76
	v_lshlrev_b32_e32 v98, 16, v77
	v_mul_f32_e32 v76, v95, v95
	v_mul_f32_e32 v77, v99, v99
	v_fmac_f32_e32 v76, v94, v94
	v_fmac_f32_e32 v77, v98, v98
	v_add_f32_e32 v76, v76, v77
	v_and_b32_e32 v79, 0xffff0000, v74
	v_and_b32_e32 v77, 0xffff0000, v75
	v_add_f32_e32 v154, v78, v76
	v_lshlrev_b32_e32 v78, 16, v74
	v_lshlrev_b32_e32 v76, 16, v75
	v_mul_f32_e32 v74, v79, v79
	v_mul_f32_e32 v75, v77, v77
	v_fmac_f32_e32 v74, v78, v78
	v_fmac_f32_e32 v75, v76, v76
	v_and_b32_e32 v129, 0xffff0000, v108
	v_and_b32_e32 v131, 0xffff0000, v109
	v_add_f32_e32 v74, v74, v75
	v_lshlrev_b32_e32 v128, 16, v108
	v_lshlrev_b32_e32 v130, 16, v109
	v_mul_f32_e32 v75, v129, v129
	v_mul_f32_e32 v108, v131, v131
	v_fmac_f32_e32 v75, v128, v128
	v_fmac_f32_e32 v108, v130, v130
	v_add_f32_e32 v75, v75, v108
	v_lshlrev_b32_e32 v116, 16, v118
	v_and_b32_e32 v117, 0xffff0000, v118
	v_lshlrev_b32_e32 v118, 16, v119
	v_and_b32_e32 v119, 0xffff0000, v119
	v_add_f32_e32 v74, v74, v75
	v_mul_f32_e32 v75, v117, v117
	v_mul_f32_e32 v108, v119, v119
	v_fmac_f32_e32 v75, v116, v116
	v_fmac_f32_e32 v108, v118, v118
	v_add_f32_e32 v75, v75, v108
	v_lshlrev_b32_e32 v108, 16, v110
	v_and_b32_e32 v109, 0xffff0000, v110
	v_lshlrev_b32_e32 v110, 16, v111
	v_and_b32_e32 v111, 0xffff0000, v111
	v_add_f32_e32 v74, v74, v75
	v_mul_f32_e32 v75, v109, v109
	v_mul_f32_e32 v124, v111, v111
	v_fmac_f32_e32 v75, v108, v108
	v_fmac_f32_e32 v124, v110, v110
	v_add_f32_e32 v75, v75, v124
	v_and_b32_e32 v149, 0xffff0000, v114
	v_and_b32_e32 v145, 0xffff0000, v115
	v_and_b32_e32 v137, 0xffff0000, v112
	v_and_b32_e32 v139, 0xffff0000, v113
	v_add_f32_e32 v74, v74, v75
	v_lshlrev_b32_e32 v148, 16, v114
	v_lshlrev_b32_e32 v144, 16, v115
	v_mul_f32_e32 v75, v149, v149
	v_mul_f32_e32 v114, v145, v145
	v_lshlrev_b32_e32 v136, 16, v112
	v_lshlrev_b32_e32 v138, 16, v113
	v_mul_f32_e32 v112, v137, v137
	v_mul_f32_e32 v113, v139, v139
	v_fmac_f32_e32 v75, v148, v148
	v_fmac_f32_e32 v114, v144, v144
	v_fmac_f32_e32 v112, v136, v136
	v_fmac_f32_e32 v113, v138, v138
	v_add_f32_e32 v75, v75, v114
	v_add_f32_e32 v112, v112, v113
	v_and_b32_e32 v113, 0xffff0000, v70
	v_and_b32_e32 v115, 0xffff0000, v71
	v_and_b32_e32 v153, 0xffff0000, v68
	v_and_b32_e32 v151, 0xffff0000, v69
	v_add_f32_e32 v75, v75, v112
	v_lshlrev_b32_e32 v112, 16, v70
	v_lshlrev_b32_e32 v114, 16, v71
	v_mul_f32_e32 v70, v113, v113
	v_mul_f32_e32 v71, v115, v115
	v_lshlrev_b32_e32 v152, 16, v68
	v_lshlrev_b32_e32 v150, 16, v69
	v_mul_f32_e32 v68, v153, v153
	v_mul_f32_e32 v69, v151, v151
	v_fmac_f32_e32 v70, v112, v112
	v_fmac_f32_e32 v71, v114, v114
	v_fmac_f32_e32 v68, v152, v152
	v_fmac_f32_e32 v69, v150, v150
	s_waitcnt vmcnt(5)
	v_and_b32_e32 v141, 0xffff0000, v132
	v_and_b32_e32 v143, 0xffff0000, v133
	v_add_f32_e32 v70, v70, v71
	v_add_f32_e32 v68, v68, v69
	v_lshlrev_b32_e32 v140, 16, v132
	v_lshlrev_b32_e32 v142, 16, v133
	v_mul_f32_e32 v69, v141, v141
	v_mul_f32_e32 v71, v143, v143
	v_fmac_f32_e32 v69, v140, v140
	v_fmac_f32_e32 v71, v142, v142
	v_add_f32_e32 v69, v69, v71
	s_waitcnt vmcnt(3)
	v_and_b32_e32 v133, 0xffff0000, v120
	v_and_b32_e32 v135, 0xffff0000, v121
	v_add_f32_e32 v68, v68, v69
	v_lshlrev_b32_e32 v132, 16, v120
	v_lshlrev_b32_e32 v134, 16, v121
	v_mul_f32_e32 v69, v133, v133
	v_mul_f32_e32 v71, v135, v135
	v_fmac_f32_e32 v69, v132, v132
	v_fmac_f32_e32 v71, v134, v134
	v_add_f32_e32 v69, v69, v71
	s_waitcnt vmcnt(1)
	v_lshlrev_b32_e32 v120, 16, v122
	v_and_b32_e32 v121, 0xffff0000, v122
	v_lshlrev_b32_e32 v122, 16, v123
	v_and_b32_e32 v123, 0xffff0000, v123
	v_add_f32_e32 v68, v68, v69
	v_mul_f32_e32 v69, v121, v121
	v_mul_f32_e32 v71, v123, v123
	v_fmac_f32_e32 v69, v120, v120
	v_fmac_f32_e32 v71, v122, v122
	v_add_f32_e32 v69, v69, v71
	v_add_f32_e32 v68, v68, v69
	ds_bpermute_b32 v69, v97, v154
	v_and_b32_e32 v125, 0xffff0000, v72
	v_and_b32_e32 v127, 0xffff0000, v73
	v_lshlrev_b32_e32 v124, 16, v72
	v_lshlrev_b32_e32 v126, 16, v73
	s_waitcnt lgkmcnt(0)
	v_add_f32_e32 v69, v154, v69
	ds_bpermute_b32 v71, v147, v69
	v_mul_f32_e32 v72, v125, v125
	v_mul_f32_e32 v73, v127, v127
	v_fmac_f32_e32 v72, v124, v124
	v_fmac_f32_e32 v73, v126, v126
	s_waitcnt lgkmcnt(0)
	v_add_f32_e32 v69, v69, v71
	ds_bpermute_b32 v71, v155, v69
	v_add_f32_e32 v72, v72, v73
	v_add_f32_e32 v72, v75, v72
	v_add_f32_e32 v70, v72, v70
	s_waitcnt lgkmcnt(0)
	v_add_f32_e32 v69, v69, v71
	ds_bpermute_b32 v71, v157, v69
	s_waitcnt lgkmcnt(0)
	v_add_f32_e32 v69, v69, v71
	ds_bpermute_b32 v71, v159, v69
	s_waitcnt lgkmcnt(0)
	v_add_f32_e32 v69, v69, v71
	ds_bpermute_b32 v71, v161, v69
	s_waitcnt lgkmcnt(0)
	v_add_f32_e32 v69, v69, v71
	v_fmamk_f32 v69, v69, 0x3a800000, v177
	v_cmp_gt_f32_e32 vcc, s53, v69
	v_mul_f32_e32 v71, 0x4f800000, v69
	s_nop 0
	v_cndmask_b32_e32 v69, v69, v71, vcc
	v_sqrt_f32_e32 v71, v69
	s_nop 0
	v_add_u32_e32 v72, -1, v71
	v_fma_f32 v73, -v72, v71, v69
	v_cmp_ge_f32_e64 s[4:5], 0, v73
	v_add_u32_e32 v73, 1, v71
	s_nop 0
	v_cndmask_b32_e64 v72, v71, v72, s[4:5]
	v_fma_f32 v71, -v73, v71, v69
	v_cmp_lt_f32_e64 s[4:5], 0, v71
	s_nop 1
	v_cndmask_b32_e64 v71, v72, v73, s[4:5]
	v_mul_f32_e32 v72, 0x37800000, v71
	v_cndmask_b32_e32 v71, v71, v72, vcc
	v_cmp_class_f32_e32 vcc, v69, v234
	s_nop 1
	v_cndmask_b32_e32 v69, v71, v69, vcc
	v_div_scale_f32 v71, s[2:3], v69, v69, 1.0
	v_rcp_f32_e32 v72, v71
	s_nop 0
	v_fma_f32 v73, -v71, v72, 1.0
	v_fmac_f32_e32 v72, v73, v72
	v_div_scale_f32 v73, vcc, 1.0, v69, 1.0
	v_mul_f32_e32 v75, v73, v72
	v_fma_f32 v154, -v71, v75, v73
	v_fmac_f32_e32 v75, v154, v72
	v_fma_f32 v71, -v71, v75, v73
	v_div_fmas_f32 v71, v71, v72, v75
	v_div_fixup_f32 v154, v71, v69, 1.0
	ds_bpermute_b32 v69, v97, v74
	v_pk_mul_f32 v[66:67], v[154:155], v[66:67] op_sel_hi:[0,1]
	v_pk_mul_f32 v[64:65], v[154:155], v[64:65] op_sel_hi:[0,1]
	s_waitcnt lgkmcnt(0)
	v_add_f32_e32 v69, v74, v69
	ds_bpermute_b32 v71, v147, v69
	s_waitcnt lgkmcnt(0)
	v_add_f32_e32 v69, v69, v71
	ds_bpermute_b32 v71, v155, v69
	s_waitcnt lgkmcnt(0)
	v_add_f32_e32 v69, v69, v71
	ds_bpermute_b32 v71, v157, v69
	s_waitcnt lgkmcnt(0)
	v_add_f32_e32 v69, v69, v71
	ds_bpermute_b32 v71, v159, v69
	s_waitcnt lgkmcnt(0)
	v_add_f32_e32 v69, v69, v71
	ds_bpermute_b32 v71, v161, v69
	s_waitcnt lgkmcnt(0)
	v_add_f32_e32 v69, v69, v71
	v_fmamk_f32 v69, v69, 0x3a800000, v177
	v_cmp_gt_f32_e32 vcc, s53, v69
	v_mul_f32_e32 v71, 0x4f800000, v69
	s_nop 0
	v_cndmask_b32_e32 v69, v69, v71, vcc
	v_sqrt_f32_e32 v71, v69
	s_nop 0
	v_add_u32_e32 v72, -1, v71
	v_fma_f32 v73, -v72, v71, v69
	v_cmp_ge_f32_e64 s[4:5], 0, v73
	v_add_u32_e32 v73, 1, v71
	s_nop 0
	v_cndmask_b32_e64 v72, v71, v72, s[4:5]
	v_fma_f32 v71, -v73, v71, v69
	v_cmp_lt_f32_e64 s[4:5], 0, v71
	s_nop 1
	v_cndmask_b32_e64 v71, v72, v73, s[4:5]
	v_mul_f32_e32 v72, 0x37800000, v71
	v_cndmask_b32_e32 v71, v71, v72, vcc
	v_cmp_class_f32_e32 vcc, v69, v234
	s_nop 1
	v_cndmask_b32_e32 v69, v71, v69, vcc
	v_div_scale_f32 v71, s[2:3], v69, v69, 1.0
	v_rcp_f32_e32 v72, v71
	s_nop 0
	v_fma_f32 v73, -v71, v72, 1.0
	v_fmac_f32_e32 v72, v73, v72
	v_div_scale_f32 v73, vcc, 1.0, v69, 1.0
	v_mul_f32_e32 v74, v73, v72
	v_fma_f32 v75, -v71, v74, v73
	v_fmac_f32_e32 v74, v75, v72
	v_fma_f32 v71, -v71, v74, v73
	v_div_fmas_f32 v71, v71, v72, v74
	v_div_fixup_f32 v156, v71, v69, 1.0
	ds_bpermute_b32 v69, v97, v70
	s_waitcnt lgkmcnt(0)
	v_add_f32_e32 v69, v70, v69
	ds_bpermute_b32 v70, v147, v69
	s_waitcnt lgkmcnt(0)
	v_add_f32_e32 v69, v69, v70
	ds_bpermute_b32 v70, v155, v69
	s_waitcnt lgkmcnt(0)
	v_add_f32_e32 v69, v69, v70
	ds_bpermute_b32 v70, v157, v69
	s_waitcnt lgkmcnt(0)
	v_add_f32_e32 v69, v69, v70
	ds_bpermute_b32 v70, v159, v69
	s_waitcnt lgkmcnt(0)
	v_add_f32_e32 v69, v69, v70
	ds_bpermute_b32 v70, v161, v69
	s_waitcnt lgkmcnt(0)
	v_add_f32_e32 v69, v69, v70
	v_fmamk_f32 v69, v69, 0x3a800000, v177
	v_cmp_gt_f32_e32 vcc, s53, v69
	v_mul_f32_e32 v70, 0x4f800000, v69
	s_nop 0
	v_cndmask_b32_e32 v69, v69, v70, vcc
	v_sqrt_f32_e32 v70, v69
	s_nop 0
	v_add_u32_e32 v71, -1, v70
	v_fma_f32 v72, -v71, v70, v69
	v_cmp_ge_f32_e64 s[4:5], 0, v72
	v_add_u32_e32 v72, 1, v70
	s_nop 0
	v_cndmask_b32_e64 v71, v70, v71, s[4:5]
	v_fma_f32 v70, -v72, v70, v69
	v_cmp_lt_f32_e64 s[4:5], 0, v70
	s_nop 1
	v_cndmask_b32_e64 v70, v71, v72, s[4:5]
	v_mul_f32_e32 v71, 0x37800000, v70
	v_cndmask_b32_e32 v70, v70, v71, vcc
	v_cmp_class_f32_e32 vcc, v69, v234
	s_nop 1
	v_cndmask_b32_e32 v69, v70, v69, vcc
	v_div_scale_f32 v70, s[2:3], v69, v69, 1.0
	v_rcp_f32_e32 v71, v70
	s_nop 0
	v_fma_f32 v72, -v70, v71, 1.0
	v_fmac_f32_e32 v71, v72, v71
	v_div_scale_f32 v72, vcc, 1.0, v69, 1.0
	v_mul_f32_e32 v73, v72, v71
	v_fma_f32 v74, -v70, v73, v72
	v_fmac_f32_e32 v73, v74, v71
	v_fma_f32 v70, -v70, v73, v72
	v_div_fmas_f32 v70, v70, v71, v73
	v_div_fixup_f32 v158, v70, v69, 1.0
	ds_bpermute_b32 v69, v97, v68
	s_waitcnt lgkmcnt(0)
	v_add_f32_e32 v68, v68, v69
	ds_bpermute_b32 v69, v147, v68
	s_waitcnt lgkmcnt(0)
	v_add_f32_e32 v68, v68, v69
	ds_bpermute_b32 v69, v155, v68
	s_waitcnt lgkmcnt(0)
	v_add_f32_e32 v68, v68, v69
	ds_bpermute_b32 v69, v157, v68
	s_waitcnt lgkmcnt(0)
	v_add_f32_e32 v68, v68, v69
	ds_bpermute_b32 v69, v159, v68
	s_waitcnt lgkmcnt(0)
	v_add_f32_e32 v68, v68, v69
	ds_bpermute_b32 v69, v161, v68
	s_waitcnt lgkmcnt(0)
	v_add_f32_e32 v68, v68, v69
	v_fmamk_f32 v68, v68, 0x3a800000, v177
	v_cmp_gt_f32_e32 vcc, s53, v68
	v_mul_f32_e32 v69, 0x4f800000, v68
	s_nop 0
	v_cndmask_b32_e32 v68, v68, v69, vcc
	v_sqrt_f32_e32 v69, v68
	s_nop 0
	v_add_u32_e32 v70, -1, v69
	v_fma_f32 v71, -v70, v69, v68
	v_cmp_ge_f32_e64 s[4:5], 0, v71
	v_add_u32_e32 v71, 1, v69
	s_nop 0
	v_cndmask_b32_e64 v70, v69, v70, s[4:5]
	v_fma_f32 v69, -v71, v69, v68
	v_cmp_lt_f32_e64 s[4:5], 0, v69
	s_nop 1
	v_cndmask_b32_e64 v69, v70, v71, s[4:5]
	v_mul_f32_e32 v70, 0x37800000, v69
	v_cndmask_b32_e32 v69, v69, v70, vcc
	v_cmp_class_f32_e32 vcc, v68, v234
	s_nop 1
	v_cndmask_b32_e32 v68, v69, v68, vcc
	v_div_scale_f32 v69, s[2:3], v68, v68, 1.0
	v_rcp_f32_e32 v70, v69
	s_nop 0
	v_fma_f32 v71, -v69, v70, 1.0
	v_fmac_f32_e32 v70, v71, v70
	v_div_scale_f32 v71, vcc, 1.0, v68, 1.0
	v_mul_f32_e32 v72, v71, v70
	v_fma_f32 v73, -v69, v72, v71
	v_fmac_f32_e32 v72, v73, v70
	v_fma_f32 v69, -v69, v72, v71
	v_div_fmas_f32 v69, v69, v70, v72
	v_div_fixup_f32 v160, v69, v68, 1.0
	global_load_dwordx4 v[68:71], v[86:87], off
	v_add_co_u32_e32 v164, vcc, s79, v162
	s_waitcnt vmcnt(0)
	v_pk_fma_f32 v[74:75], v[64:65], v[70:71], v[42:43]
	v_addc_co_u32_e32 v165, vcc, 0, v163, vcc
	v_pk_fma_f32 v[72:73], v[66:67], v[68:69], v[40:41]
	v_pk_mul_f32 v[40:41], v[156:157], v[78:79] op_sel_hi:[0,1]
	v_pk_mul_f32 v[42:43], v[156:157], v[76:77] op_sel_hi:[0,1]
	v_add_co_u32_e32 v166, vcc, s23, v162
	v_pk_fma_f32 v[66:67], v[42:43], v[70:71], v[50:51]
	v_pk_fma_f32 v[64:65], v[40:41], v[68:69], v[48:49]
	v_addc_co_u32_e32 v167, vcc, 0, v163, vcc
	v_pk_mul_f32 v[40:41], v[158:159], v[148:149] op_sel_hi:[0,1]
	v_pk_mul_f32 v[42:43], v[158:159], v[144:145] op_sel_hi:[0,1]
	v_pk_fma_f32 v[78:79], v[70:71], v[42:43], v[54:55]
	v_pk_fma_f32 v[76:77], v[68:69], v[40:41], v[52:53]
	v_pk_mul_f32 v[40:41], v[160:161], v[152:153] op_sel_hi:[0,1]
	v_pk_mul_f32 v[42:43], v[160:161], v[150:151] op_sel_hi:[0,1]
	v_add_co_u32_e32 v144, vcc, s24, v162
	v_pk_fma_f32 v[62:63], v[70:71], v[42:43], v[62:63]
	v_pk_fma_f32 v[60:61], v[68:69], v[40:41], v[60:61]
	v_addc_co_u32_e32 v145, vcc, 0, v163, vcc
	global_store_dwordx4 v[162:163], v[72:75], off sc1
	global_store_dwordx4 v[166:167], v[64:67], off offset:-4096 sc1
	global_store_dwordx4 v[166:167], v[76:79], off sc1
	global_store_dwordx4 v[144:145], v[60:63], off sc1
	global_load_dwordx4 v[40:43], v[86:87], off offset:1024
	v_pk_mul_f32 v[48:49], v[154:155], v[106:107] op_sel_hi:[0,1]
	v_pk_mul_f32 v[50:51], v[154:155], v[104:105] op_sel_hi:[0,1]
	s_andn2_b64 vcc, exec, s[16:17]
	s_waitcnt vmcnt(0)
	v_pk_fma_f32 v[68:69], v[50:51], v[40:41], v[20:21]
	v_pk_fma_f32 v[70:71], v[48:49], v[42:43], v[22:23]
	v_pk_mul_f32 v[20:21], v[156:157], v[130:131] op_sel_hi:[0,1]
	v_pk_mul_f32 v[22:23], v[156:157], v[128:129] op_sel_hi:[0,1]
	v_pk_fma_f32 v[52:53], v[22:23], v[40:41], v[32:33]
	v_pk_fma_f32 v[54:55], v[20:21], v[42:43], v[34:35]
	v_pk_mul_f32 v[20:21], v[158:159], v[138:139] op_sel_hi:[0,1]
	v_pk_mul_f32 v[22:23], v[158:159], v[136:137] op_sel_hi:[0,1]
	v_pk_fma_f32 v[48:49], v[22:23], v[40:41], v[36:37]
	v_pk_fma_f32 v[50:51], v[20:21], v[42:43], v[38:39]
	v_pk_mul_f32 v[20:21], v[160:161], v[142:143] op_sel_hi:[0,1]
	v_pk_mul_f32 v[22:23], v[160:161], v[140:141] op_sel_hi:[0,1]
	v_pk_fma_f32 v[40:41], v[40:41], v[22:23], v[56:57]
	v_pk_fma_f32 v[42:43], v[42:43], v[20:21], v[58:59]
	global_store_dwordx4 v[162:163], v[68:71], off offset:1024 sc1
	global_store_dwordx4 v[164:165], v[52:55], off offset:1024 sc1
	global_store_dwordx4 v[166:167], v[48:51], off offset:1024 sc1
	global_store_dwordx4 v[144:145], v[40:43], off offset:1024 sc1
	global_load_dwordx4 v[56:59], v[86:87], off offset:2048
	v_pk_mul_f32 v[20:21], v[154:155], v[102:103] op_sel_hi:[0,1]
	v_pk_mul_f32 v[22:23], v[154:155], v[100:101] op_sel_hi:[0,1]
	s_waitcnt vmcnt(0)
	v_pk_fma_f32 v[36:37], v[22:23], v[56:57], v[12:13]
	v_pk_fma_f32 v[38:39], v[20:21], v[58:59], v[14:15]
	v_pk_mul_f32 v[12:13], v[156:157], v[118:119] op_sel_hi:[0,1]
	v_pk_mul_f32 v[14:15], v[156:157], v[116:117] op_sel_hi:[0,1]
	v_pk_fma_f32 v[32:33], v[14:15], v[56:57], v[16:17]
	v_pk_fma_f32 v[34:35], v[12:13], v[58:59], v[18:19]
	v_pk_mul_f32 v[12:13], v[158:159], v[126:127] op_sel_hi:[0,1]
	v_pk_mul_f32 v[14:15], v[158:159], v[124:125] op_sel_hi:[0,1]
	v_pk_fma_f32 v[20:21], v[14:15], v[56:57], v[24:25]
	v_pk_fma_f32 v[22:23], v[12:13], v[58:59], v[26:27]
	v_pk_mul_f32 v[12:13], v[160:161], v[134:135] op_sel_hi:[0,1]
	v_pk_mul_f32 v[14:15], v[160:161], v[132:133] op_sel_hi:[0,1]
	v_pk_fma_f32 v[16:17], v[14:15], v[56:57], v[44:45]
	v_pk_fma_f32 v[18:19], v[12:13], v[58:59], v[46:47]
	global_store_dwordx4 v[162:163], v[36:39], off offset:2048 sc1
	global_store_dwordx4 v[164:165], v[32:35], off offset:2048 sc1
	global_store_dwordx4 v[166:167], v[20:23], off offset:2048 sc1
	global_store_dwordx4 v[144:145], v[16:19], off offset:2048 sc1
	global_load_dwordx4 v[24:27], v[86:87], off offset:3072
	v_pk_mul_f32 v[14:15], v[154:155], v[98:99] op_sel_hi:[0,1]
	v_pk_mul_f32 v[12:13], v[154:155], v[94:95] op_sel_hi:[0,1]
	s_waitcnt vmcnt(0)
	v_pk_fma_f32 v[12:13], v[12:13], v[24:25], v[0:1]
	v_pk_fma_f32 v[14:15], v[14:15], v[26:27], v[2:3]
	v_pk_mul_f32 v[0:1], v[156:157], v[110:111] op_sel_hi:[0,1]
	v_pk_mul_f32 v[2:3], v[156:157], v[108:109] op_sel_hi:[0,1]
	v_pk_fma_f32 v[8:9], v[2:3], v[24:25], v[8:9]
	v_pk_fma_f32 v[10:11], v[0:1], v[26:27], v[10:11]
	v_pk_mul_f32 v[0:1], v[158:159], v[114:115] op_sel_hi:[0,1]
	v_pk_mul_f32 v[2:3], v[158:159], v[112:113] op_sel_hi:[0,1]
	v_pk_fma_f32 v[4:5], v[2:3], v[24:25], v[4:5]
	v_pk_fma_f32 v[6:7], v[0:1], v[26:27], v[6:7]
	v_pk_mul_f32 v[2:3], v[160:161], v[122:123] op_sel_hi:[0,1]
	v_pk_mul_f32 v[0:1], v[160:161], v[120:121] op_sel_hi:[0,1]
	v_pk_fma_f32 v[0:1], v[0:1], v[24:25], v[28:29]
	v_pk_fma_f32 v[2:3], v[2:3], v[26:27], v[30:31]
	global_store_dwordx4 v[162:163], v[12:15], off offset:3072 sc1
	global_store_dwordx4 v[164:165], v[8:11], off offset:3072 sc1
	global_store_dwordx4 v[166:167], v[4:7], off offset:3072 sc1
	global_store_dwordx4 v[144:145], v[0:3], off offset:3072 sc1
	s_cbranch_vccnz .LBB0_1847
	v_mul_f32_e32 v24, v61, v61
	v_mul_f32_e32 v25, v63, v63
	v_fmac_f32_e32 v24, v60, v60
	v_fmac_f32_e32 v25, v62, v62
	v_add_f32_e32 v24, v24, v25
	v_mul_f32_e32 v25, v41, v41
	v_mul_f32_e32 v26, v43, v43
	v_fmac_f32_e32 v25, v40, v40
	v_fmac_f32_e32 v26, v42, v42
	v_add_f32_e32 v25, v25, v26
	v_add_f32_e32 v24, v24, v25
	v_mul_f32_e32 v25, v17, v17
	v_mul_f32_e32 v26, v19, v19
	v_fmac_f32_e32 v25, v16, v16
	v_fmac_f32_e32 v26, v18, v18
	v_add_f32_e32 v25, v25, v26
	v_add_f32_e32 v24, v24, v25
	v_mul_f32_e32 v25, v1, v1
	v_mul_f32_e32 v26, v3, v3
	v_fmac_f32_e32 v25, v0, v0
	v_fmac_f32_e32 v26, v2, v2
	v_add_f32_e32 v25, v25, v26
	v_add_f32_e32 v24, v24, v25
	v_mul_f32_e32 v25, v77, v77
	v_mul_f32_e32 v26, v79, v79
	v_fmac_f32_e32 v25, v76, v76
	v_fmac_f32_e32 v26, v78, v78
	v_add_f32_e32 v25, v25, v26
	v_mul_f32_e32 v26, v49, v49
	v_mul_f32_e32 v27, v51, v51
	v_fmac_f32_e32 v26, v48, v48
	v_fmac_f32_e32 v27, v50, v50
	v_add_f32_e32 v26, v26, v27
	v_add_f32_e32 v25, v25, v26
	v_mul_f32_e32 v26, v21, v21
	v_mul_f32_e32 v27, v23, v23
	v_fmac_f32_e32 v26, v20, v20
	v_fmac_f32_e32 v27, v22, v22
	v_add_f32_e32 v26, v26, v27
	v_add_f32_e32 v25, v25, v26
	v_mul_f32_e32 v26, v5, v5
	v_mul_f32_e32 v27, v7, v7
	v_fmac_f32_e32 v26, v4, v4
	v_fmac_f32_e32 v27, v6, v6
	v_add_f32_e32 v26, v26, v27
	v_add_f32_e32 v25, v25, v26
	v_mul_f32_e32 v26, v65, v65
	v_mul_f32_e32 v27, v67, v67
	v_fmac_f32_e32 v26, v64, v64
	v_fmac_f32_e32 v27, v66, v66
	v_add_f32_e32 v26, v26, v27
	v_mul_f32_e32 v27, v53, v53
	v_mul_f32_e32 v28, v55, v55
	v_fmac_f32_e32 v27, v52, v52
	v_fmac_f32_e32 v28, v54, v54
	v_add_f32_e32 v27, v27, v28
	v_add_f32_e32 v26, v26, v27
	v_mul_f32_e32 v27, v33, v33
	v_mul_f32_e32 v28, v35, v35
	v_fmac_f32_e32 v27, v32, v32
	v_fmac_f32_e32 v28, v34, v34
	v_add_f32_e32 v27, v27, v28
	v_add_f32_e32 v26, v26, v27
	v_mul_f32_e32 v27, v9, v9
	v_mul_f32_e32 v28, v11, v11
	v_fmac_f32_e32 v27, v8, v8
	v_fmac_f32_e32 v28, v10, v10
	v_add_f32_e32 v27, v27, v28
	v_add_f32_e32 v26, v26, v27
	v_mul_f32_e32 v27, v73, v73
	v_mul_f32_e32 v28, v75, v75
	v_fmac_f32_e32 v27, v72, v72
	v_fmac_f32_e32 v28, v74, v74
	v_add_f32_e32 v27, v27, v28
	v_mul_f32_e32 v28, v69, v69
	v_mul_f32_e32 v29, v71, v71
	v_fmac_f32_e32 v28, v68, v68
	v_fmac_f32_e32 v29, v70, v70
	v_add_f32_e32 v28, v28, v29
	v_add_f32_e32 v27, v27, v28
	v_mul_f32_e32 v28, v37, v37
	v_mul_f32_e32 v29, v39, v39
	v_fmac_f32_e32 v28, v36, v36
	v_fmac_f32_e32 v29, v38, v38
	v_add_f32_e32 v28, v28, v29
	v_add_f32_e32 v27, v27, v28
	v_mul_f32_e32 v28, v13, v13
	v_mul_f32_e32 v29, v15, v15
	v_fmac_f32_e32 v28, v12, v12
	v_fmac_f32_e32 v29, v14, v14
	v_add_f32_e32 v28, v28, v29
	v_add_f32_e32 v27, v27, v28
	ds_bpermute_b32 v28, v97, v27
	s_lshl_b64 s[20:21], s[18:19], 10
	s_waitcnt lgkmcnt(0)
	v_add_f32_e32 v27, v27, v28
	ds_bpermute_b32 v28, v147, v27
	s_waitcnt lgkmcnt(0)
	v_add_f32_e32 v27, v27, v28
	ds_bpermute_b32 v28, v155, v27
	s_waitcnt lgkmcnt(0)
	v_add_f32_e32 v27, v27, v28
	ds_bpermute_b32 v28, v157, v27
	s_waitcnt lgkmcnt(0)
	v_add_f32_e32 v27, v27, v28
	ds_bpermute_b32 v28, v159, v27
	s_waitcnt lgkmcnt(0)
	v_add_f32_e32 v27, v27, v28
	ds_bpermute_b32 v28, v161, v27
	s_waitcnt lgkmcnt(0)
	v_add_f32_e32 v27, v27, v28
	v_fmamk_f32 v27, v27, 0x3a800000, v177
	v_cmp_gt_f32_e32 vcc, s53, v27
	v_mul_f32_e32 v28, 0x4f800000, v27
	s_nop 0
	v_cndmask_b32_e32 v27, v27, v28, vcc
	v_sqrt_f32_e32 v28, v27
	s_nop 0
	v_add_u32_e32 v29, -1, v28
	v_fma_f32 v30, -v29, v28, v27
	v_cmp_ge_f32_e64 s[4:5], 0, v30
	v_add_u32_e32 v30, 1, v28
	s_nop 0
	v_cndmask_b32_e64 v29, v28, v29, s[4:5]
	v_fma_f32 v28, -v30, v28, v27
	v_cmp_lt_f32_e64 s[4:5], 0, v28
	s_nop 1
	v_cndmask_b32_e64 v28, v29, v30, s[4:5]
	v_mul_f32_e32 v29, 0x37800000, v28
	v_cndmask_b32_e32 v28, v28, v29, vcc
	v_cmp_class_f32_e32 vcc, v27, v234
	s_nop 1
	v_cndmask_b32_e32 v27, v28, v27, vcc
	v_div_scale_f32 v28, s[2:3], v27, v27, 1.0
	v_rcp_f32_e32 v29, v28
	s_nop 0
	v_fma_f32 v30, -v28, v29, 1.0
	v_fmac_f32_e32 v29, v30, v29
	v_div_scale_f32 v30, vcc, 1.0, v27, 1.0
	v_mul_f32_e32 v31, v30, v29
	v_fma_f32 v44, -v28, v31, v30
	v_fmac_f32_e32 v31, v44, v29
	v_fma_f32 v28, -v28, v31, v30
	v_div_fmas_f32 v28, v28, v29, v31
	v_div_fixup_f32 v44, v28, v27, 1.0
	ds_bpermute_b32 v27, v97, v26
	v_mul_f32_e32 v36, v36, v44
	v_mul_f32_e32 v37, v37, v44
	v_mul_f32_e32 v12, v12, v44
	v_mul_f32_e32 v13, v13, v44
	s_waitcnt lgkmcnt(0)
	v_add_f32_e32 v26, v26, v27
	ds_bpermute_b32 v27, v147, v26
	s_waitcnt lgkmcnt(0)
	v_add_f32_e32 v26, v26, v27
	ds_bpermute_b32 v27, v155, v26
	s_waitcnt lgkmcnt(0)
	v_add_f32_e32 v26, v26, v27
	ds_bpermute_b32 v27, v157, v26
	s_waitcnt lgkmcnt(0)
	v_add_f32_e32 v26, v26, v27
	ds_bpermute_b32 v27, v159, v26
	s_waitcnt lgkmcnt(0)
	v_add_f32_e32 v26, v26, v27
	ds_bpermute_b32 v27, v161, v26
	s_waitcnt lgkmcnt(0)
	v_add_f32_e32 v26, v26, v27
	v_fmamk_f32 v26, v26, 0x3a800000, v177
	v_cmp_gt_f32_e32 vcc, s53, v26
	v_mul_f32_e32 v27, 0x4f800000, v26
	s_nop 0
	v_cndmask_b32_e32 v26, v26, v27, vcc
	v_sqrt_f32_e32 v27, v26
	s_nop 0
	v_add_u32_e32 v28, -1, v27
	v_fma_f32 v29, -v28, v27, v26
	v_cmp_ge_f32_e64 s[4:5], 0, v29
	v_add_u32_e32 v29, 1, v27
	s_nop 0
	v_cndmask_b32_e64 v28, v27, v28, s[4:5]
	v_fma_f32 v27, -v29, v27, v26
	v_cmp_lt_f32_e64 s[4:5], 0, v27
	s_nop 1
	v_cndmask_b32_e64 v27, v28, v29, s[4:5]
	v_mul_f32_e32 v28, 0x37800000, v27
	v_cndmask_b32_e32 v27, v27, v28, vcc
	v_cmp_class_f32_e32 vcc, v26, v234
	s_nop 1
	v_cndmask_b32_e32 v26, v27, v26, vcc
	v_div_scale_f32 v27, s[2:3], v26, v26, 1.0
	v_rcp_f32_e32 v28, v27
	s_nop 0
	v_fma_f32 v29, -v27, v28, 1.0
	v_fmac_f32_e32 v28, v29, v28
	v_div_scale_f32 v29, vcc, 1.0, v26, 1.0
	v_mul_f32_e32 v30, v29, v28
	v_fma_f32 v31, -v27, v30, v29
	v_fmac_f32_e32 v30, v31, v28
	v_fma_f32 v27, -v27, v30, v29
	v_div_fmas_f32 v27, v27, v28, v30
	v_div_fixup_f32 v45, v27, v26, 1.0
	ds_bpermute_b32 v26, v97, v25
	v_mul_f32_e32 v31, v73, v44
	v_mul_f32_e32 v52, v52, v45
	v_mul_f32_e32 v53, v53, v45
	v_mul_f32_e32 v32, v32, v45
	s_waitcnt lgkmcnt(0)
	v_add_f32_e32 v25, v25, v26
	ds_bpermute_b32 v26, v147, v25
	v_mul_f32_e32 v33, v33, v45
	v_mul_f32_e32 v8, v8, v45
	v_mul_f32_e32 v9, v9, v45
	s_waitcnt lgkmcnt(0)
	v_add_f32_e32 v25, v25, v26
	ds_bpermute_b32 v26, v155, v25
	s_waitcnt lgkmcnt(0)
	v_add_f32_e32 v25, v25, v26
	ds_bpermute_b32 v26, v157, v25
	s_waitcnt lgkmcnt(0)
	v_add_f32_e32 v25, v25, v26
	ds_bpermute_b32 v26, v159, v25
	s_waitcnt lgkmcnt(0)
	v_add_f32_e32 v25, v25, v26
	ds_bpermute_b32 v26, v161, v25
	s_waitcnt lgkmcnt(0)
	v_add_f32_e32 v25, v25, v26
	v_fmamk_f32 v25, v25, 0x3a800000, v177
	v_cmp_gt_f32_e32 vcc, s53, v25
	v_mul_f32_e32 v26, 0x4f800000, v25
	s_nop 0
	v_cndmask_b32_e32 v25, v25, v26, vcc
	v_sqrt_f32_e32 v26, v25
	s_nop 0
	v_add_u32_e32 v27, -1, v26
	v_fma_f32 v28, -v27, v26, v25
	v_cmp_ge_f32_e64 s[4:5], 0, v28
	v_add_u32_e32 v28, 1, v26
	s_nop 0
	v_cndmask_b32_e64 v27, v26, v27, s[4:5]
	v_fma_f32 v26, -v28, v26, v25
	v_cmp_lt_f32_e64 s[4:5], 0, v26
	s_nop 1
	v_cndmask_b32_e64 v26, v27, v28, s[4:5]
	v_mul_f32_e32 v27, 0x37800000, v26
	v_cndmask_b32_e32 v26, v26, v27, vcc
	v_cmp_class_f32_e32 vcc, v25, v234
	s_nop 1
	v_cndmask_b32_e32 v25, v26, v25, vcc
	v_div_scale_f32 v26, s[2:3], v25, v25, 1.0
	v_rcp_f32_e32 v27, v26
	s_nop 0
	v_fma_f32 v28, -v26, v27, 1.0
	v_fmac_f32_e32 v27, v28, v27
	v_div_scale_f32 v28, vcc, 1.0, v25, 1.0
	v_mul_f32_e32 v29, v28, v27
	v_fma_f32 v30, -v26, v29, v28
	v_fmac_f32_e32 v29, v30, v27
	v_fma_f32 v26, -v26, v29, v28
	v_div_fmas_f32 v26, v26, v27, v29
	v_div_fixup_f32 v46, v26, v25, 1.0
	ds_bpermute_b32 v25, v97, v24
	v_mul_f32_e32 v30, v72, v44
	v_mul_f32_e32 v48, v48, v46
	v_mul_f32_e32 v49, v49, v46
	v_mul_f32_e32 v20, v20, v46
	s_waitcnt lgkmcnt(0)
	v_add_f32_e32 v24, v24, v25
	ds_bpermute_b32 v25, v147, v24
	v_mul_f32_e32 v21, v21, v46
	v_mul_f32_e32 v4, v4, v46
	v_mul_f32_e32 v5, v5, v46
	s_waitcnt lgkmcnt(0)
	v_add_f32_e32 v24, v24, v25
	ds_bpermute_b32 v25, v155, v24
	s_waitcnt lgkmcnt(0)
	v_add_f32_e32 v24, v24, v25
	ds_bpermute_b32 v25, v157, v24
	s_waitcnt lgkmcnt(0)
	v_add_f32_e32 v24, v24, v25
	ds_bpermute_b32 v25, v159, v24
	s_waitcnt lgkmcnt(0)
	v_add_f32_e32 v24, v24, v25
	ds_bpermute_b32 v25, v161, v24
	s_waitcnt lgkmcnt(0)
	v_add_f32_e32 v24, v24, v25
	v_fmamk_f32 v24, v24, 0x3a800000, v177
	v_cmp_gt_f32_e32 vcc, s53, v24
	v_mul_f32_e32 v25, 0x4f800000, v24
	s_nop 0
	v_cndmask_b32_e32 v24, v24, v25, vcc
	v_sqrt_f32_e32 v25, v24
	s_nop 0
	v_add_u32_e32 v26, -1, v25
	v_fma_f32 v27, -v26, v25, v24
	v_cmp_ge_f32_e64 s[4:5], 0, v27
	v_add_u32_e32 v27, 1, v25
	s_nop 0
	v_cndmask_b32_e64 v26, v25, v26, s[4:5]
	v_fma_f32 v25, -v27, v25, v24
	v_cmp_lt_f32_e64 s[4:5], 0, v25
	s_nop 1
	v_cndmask_b32_e64 v25, v26, v27, s[4:5]
	v_mul_f32_e32 v26, 0x37800000, v25
	v_cndmask_b32_e32 v25, v25, v26, vcc
	v_cmp_class_f32_e32 vcc, v24, v234
	s_nop 1
	v_cndmask_b32_e32 v24, v25, v24, vcc
	v_div_scale_f32 v25, s[2:3], v24, v24, 1.0
	v_rcp_f32_e32 v26, v25
	s_nop 0
	v_fma_f32 v27, -v25, v26, 1.0
	v_fmac_f32_e32 v26, v27, v26
	v_div_scale_f32 v27, vcc, 1.0, v24, 1.0
	v_mul_f32_e32 v28, v27, v26
	v_fma_f32 v29, -v25, v28, v27
	v_fmac_f32_e32 v28, v29, v26
	v_fma_f32 v25, -v25, v28, v27
	v_div_fmas_f32 v25, v25, v26, v28
	v_div_fixup_f32 v47, v25, v24, 1.0
	global_load_dwordx4 v[24:27], v[88:89], off
	v_lshl_add_u64 v[28:29], s[20:21], 1, v[90:91]
	v_mul_f32_e32 v40, v40, v47
	v_mul_f32_e32 v16, v16, v47
	v_mul_f32_e32 v17, v17, v47
	v_mul_f32_e32 v0, v0, v47
	v_mul_f32_e32 v1, v1, v47
	s_waitcnt vmcnt(0)
	v_mul_f32_e32 v30, v30, v24
	v_mul_f32_e32 v31, v31, v25
	v_bfe_u32 v56, v30, 16, 1
	v_add3_u32 v30, v30, v56, s36
	v_bfe_u32 v56, v31, 16, 1
	v_lshrrev_b32_e32 v30, 16, v30
	v_add3_u32 v31, v31, v56, s36
	v_and_or_b32 v30, v31, s68, v30
	v_mul_f32_e32 v31, v74, v44
	v_mul_f32_e32 v31, v31, v26
	v_mul_f32_e32 v56, v75, v44
	v_mul_f32_e32 v56, v56, v27
	v_bfe_u32 v57, v31, 16, 1
	v_add3_u32 v31, v31, v57, s36
	v_bfe_u32 v57, v56, 16, 1
	v_lshrrev_b32_e32 v31, 16, v31
	v_add3_u32 v56, v56, v57, s36
	v_and_or_b32 v31, v56, s68, v31
	global_store_dwordx2 v[28:29], v[30:31], off sc1
	v_mul_f32_e32 v30, v64, v45
	v_mul_f32_e32 v30, v30, v24
	v_mul_f32_e32 v31, v65, v45
	v_mul_f32_e32 v31, v31, v25
	v_bfe_u32 v56, v30, 16, 1
	v_add3_u32 v30, v30, v56, s36
	v_bfe_u32 v56, v31, 16, 1
	v_lshrrev_b32_e32 v30, 16, v30
	v_add3_u32 v31, v31, v56, s36
	v_and_or_b32 v30, v31, s68, v30
	v_mul_f32_e32 v31, v66, v45
	v_mul_f32_e32 v31, v31, v26
	v_mul_f32_e32 v56, v67, v45
	v_mul_f32_e32 v56, v56, v27
	v_bfe_u32 v57, v31, 16, 1
	v_add3_u32 v31, v31, v57, s36
	v_bfe_u32 v57, v56, 16, 1
	v_lshrrev_b32_e32 v31, 16, v31
	v_add3_u32 v56, v56, v57, s36
	v_and_or_b32 v31, v56, s68, v31
	global_store_dwordx2 v[28:29], v[30:31], off offset:2048 sc1
	v_mul_f32_e32 v30, v76, v46
	v_mul_f32_e32 v30, v30, v24
	v_mul_f32_e32 v31, v77, v46
	v_mul_f32_e32 v31, v31, v25
	v_bfe_u32 v56, v30, 16, 1
	v_add3_u32 v30, v30, v56, s36
	v_bfe_u32 v56, v31, 16, 1
	v_lshrrev_b32_e32 v30, 16, v30
	v_add3_u32 v31, v31, v56, s36
	v_and_or_b32 v56, v31, s68, v30
	v_mul_f32_e32 v30, v78, v46
	v_mul_f32_e32 v30, v30, v26
	v_mul_f32_e32 v31, v79, v46
	v_mul_f32_e32 v31, v31, v27
	v_bfe_u32 v57, v30, 16, 1
	v_add3_u32 v30, v30, v57, s36
	v_bfe_u32 v57, v31, 16, 1
	v_lshrrev_b32_e32 v30, 16, v30
	v_add3_u32 v31, v31, v57, s36
	v_and_or_b32 v57, v31, s68, v30
	v_add_co_u32_e32 v30, vcc, s79, v28
	s_nop 1
	v_addc_co_u32_e32 v31, vcc, 0, v29, vcc
	global_store_dwordx2 v[30:31], v[56:57], off sc1
	v_mul_f32_e32 v56, v60, v47
	v_mul_f32_e32 v24, v24, v56
	v_mul_f32_e32 v56, v61, v47
	v_mul_f32_e32 v25, v25, v56
	v_bfe_u32 v56, v24, 16, 1
	v_add3_u32 v24, v24, v56, s36
	v_bfe_u32 v56, v25, 16, 1
	v_lshrrev_b32_e32 v24, 16, v24
	v_add3_u32 v25, v25, v56, s36
	v_and_or_b32 v24, v25, s68, v24
	v_mul_f32_e32 v25, v62, v47
	v_mul_f32_e32 v25, v26, v25
	v_mul_f32_e32 v26, v63, v47
	v_mul_f32_e32 v26, v27, v26
	v_bfe_u32 v27, v25, 16, 1
	v_add3_u32 v25, v25, v27, s36
	v_bfe_u32 v27, v26, 16, 1
	v_lshrrev_b32_e32 v25, 16, v25
	v_add3_u32 v26, v26, v27, s36
	v_and_or_b32 v25, v26, s68, v25
	global_store_dwordx2 v[30:31], v[24:25], off offset:2048 sc1
	global_load_dwordx4 v[24:27], v[88:89], off offset:1024
	v_mul_f32_e32 v56, v68, v44
	v_mul_f32_e32 v57, v69, v44
	s_waitcnt vmcnt(0)
	v_mul_f32_e32 v56, v56, v24
	v_mul_f32_e32 v57, v57, v25
	v_bfe_u32 v58, v56, 16, 1
	v_add3_u32 v56, v56, v58, s36
	v_bfe_u32 v58, v57, 16, 1
	v_lshrrev_b32_e32 v56, 16, v56
	v_add3_u32 v57, v57, v58, s36
	v_and_or_b32 v56, v57, s68, v56
	v_mul_f32_e32 v57, v70, v44
	v_mul_f32_e32 v57, v57, v26
	v_mul_f32_e32 v58, v71, v44
	v_mul_f32_e32 v58, v58, v27
	v_bfe_u32 v59, v57, 16, 1
	v_add3_u32 v57, v57, v59, s36
	v_bfe_u32 v59, v58, 16, 1
	v_lshrrev_b32_e32 v57, 16, v57
	v_add3_u32 v58, v58, v59, s36
	v_and_or_b32 v57, v58, s68, v57
	v_mul_f32_e32 v52, v52, v24
	global_store_dwordx2 v[28:29], v[56:57], off offset:512 sc1
	v_mul_f32_e32 v53, v53, v25
	v_bfe_u32 v56, v52, 16, 1
	v_add3_u32 v52, v52, v56, s36
	v_bfe_u32 v56, v53, 16, 1
	v_lshrrev_b32_e32 v52, 16, v52
	v_add3_u32 v53, v53, v56, s36
	v_and_or_b32 v52, v53, s68, v52
	v_mul_f32_e32 v53, v54, v45
	v_mul_f32_e32 v53, v53, v26
	v_mul_f32_e32 v54, v55, v45
	v_mul_f32_e32 v54, v54, v27
	v_bfe_u32 v55, v53, 16, 1
	v_add3_u32 v53, v53, v55, s36
	v_bfe_u32 v55, v54, 16, 1
	v_lshrrev_b32_e32 v53, 16, v53
	v_add3_u32 v54, v54, v55, s36
	v_and_or_b32 v53, v54, s68, v53
	v_mul_f32_e32 v48, v48, v24
	v_mul_f32_e32 v24, v24, v40
	v_mul_f32_e32 v40, v41, v47
	global_store_dwordx2 v[28:29], v[52:53], off offset:2560 sc1
	v_mul_f32_e32 v49, v49, v25
	v_bfe_u32 v52, v48, 16, 1
	v_mul_f32_e32 v25, v25, v40
	v_bfe_u32 v40, v24, 16, 1
	v_add3_u32 v48, v48, v52, s36
	v_bfe_u32 v52, v49, 16, 1
	v_add3_u32 v24, v24, v40, s36
	v_bfe_u32 v40, v25, 16, 1
	v_lshrrev_b32_e32 v48, 16, v48
	v_add3_u32 v49, v49, v52, s36
	v_lshrrev_b32_e32 v24, 16, v24
	v_add3_u32 v25, v25, v40, s36
	v_and_or_b32 v48, v49, s68, v48
	v_mul_f32_e32 v49, v50, v46
	v_and_or_b32 v24, v25, s68, v24
	v_mul_f32_e32 v25, v42, v47
	v_mul_f32_e32 v49, v49, v26
	v_mul_f32_e32 v50, v51, v46
	v_mul_f32_e32 v25, v26, v25
	v_mul_f32_e32 v26, v43, v47
	v_mul_f32_e32 v50, v50, v27
	v_bfe_u32 v51, v49, 16, 1
	v_mul_f32_e32 v26, v27, v26
	v_bfe_u32 v27, v25, 16, 1
	v_add3_u32 v49, v49, v51, s36
	v_bfe_u32 v51, v50, 16, 1
	v_add3_u32 v25, v25, v27, s36
	v_bfe_u32 v27, v26, 16, 1
	v_lshrrev_b32_e32 v49, 16, v49
	v_add3_u32 v50, v50, v51, s36
	v_lshrrev_b32_e32 v25, 16, v25
	v_add3_u32 v26, v26, v27, s36
	v_and_or_b32 v49, v50, s68, v49
	v_and_or_b32 v25, v26, s68, v25
	global_store_dwordx2 v[30:31], v[48:49], off offset:512 sc1
	global_store_dwordx2 v[30:31], v[24:25], off offset:2560 sc1
	global_load_dwordx4 v[24:27], v[88:89], off offset:2048
	s_waitcnt vmcnt(0)
	v_mul_f32_e32 v36, v36, v24
	v_mul_f32_e32 v37, v37, v25
	v_bfe_u32 v40, v36, 16, 1
	v_add3_u32 v36, v36, v40, s36
	v_bfe_u32 v40, v37, 16, 1
	v_lshrrev_b32_e32 v36, 16, v36
	v_add3_u32 v37, v37, v40, s36
	v_and_or_b32 v36, v37, s68, v36
	v_mul_f32_e32 v37, v38, v44
	v_mul_f32_e32 v37, v37, v26
	v_mul_f32_e32 v38, v39, v44
	v_mul_f32_e32 v38, v38, v27
	v_bfe_u32 v39, v37, 16, 1
	v_add3_u32 v37, v37, v39, s36
	v_bfe_u32 v39, v38, 16, 1
	v_lshrrev_b32_e32 v37, 16, v37
	v_add3_u32 v38, v38, v39, s36
	v_and_or_b32 v37, v38, s68, v37
	v_mul_f32_e32 v32, v32, v24
	global_store_dwordx2 v[28:29], v[36:37], off offset:1024 sc1
	v_mul_f32_e32 v33, v33, v25
	v_bfe_u32 v36, v32, 16, 1
	v_add3_u32 v32, v32, v36, s36
	v_bfe_u32 v36, v33, 16, 1
	v_lshrrev_b32_e32 v32, 16, v32
	v_add3_u32 v33, v33, v36, s36
	v_and_or_b32 v32, v33, s68, v32
	v_mul_f32_e32 v33, v34, v45
	v_mul_f32_e32 v33, v33, v26
	v_mul_f32_e32 v34, v35, v45
	v_mul_f32_e32 v34, v34, v27
	v_bfe_u32 v35, v33, 16, 1
	v_add3_u32 v33, v33, v35, s36
	v_bfe_u32 v35, v34, 16, 1
	v_lshrrev_b32_e32 v33, 16, v33
	v_add3_u32 v34, v34, v35, s36
	v_and_or_b32 v33, v34, s68, v33
	v_mul_f32_e32 v20, v20, v24
	global_store_dwordx2 v[28:29], v[32:33], off offset:3072 sc1
	v_mul_f32_e32 v21, v21, v25
	v_bfe_u32 v32, v20, 16, 1
	v_add3_u32 v20, v20, v32, s36
	v_bfe_u32 v32, v21, 16, 1
	v_lshrrev_b32_e32 v20, 16, v20
	v_add3_u32 v21, v21, v32, s36
	v_and_or_b32 v20, v21, s68, v20
	v_mul_f32_e32 v21, v22, v46
	v_mul_f32_e32 v21, v21, v26
	v_mul_f32_e32 v22, v23, v46
	v_mul_f32_e32 v22, v22, v27
	v_bfe_u32 v23, v21, 16, 1
	v_add3_u32 v21, v21, v23, s36
	v_bfe_u32 v23, v22, 16, 1
	v_lshrrev_b32_e32 v21, 16, v21
	v_add3_u32 v22, v22, v23, s36
	v_and_or_b32 v21, v22, s68, v21
	v_mul_f32_e32 v16, v16, v24
	global_store_dwordx2 v[30:31], v[20:21], off offset:1024 sc1
	v_mul_f32_e32 v17, v17, v25
	v_bfe_u32 v20, v16, 16, 1
	v_add3_u32 v16, v16, v20, s36
	v_bfe_u32 v20, v17, 16, 1
	v_lshrrev_b32_e32 v16, 16, v16
	v_add3_u32 v17, v17, v20, s36
	v_and_or_b32 v16, v17, s68, v16
	v_mul_f32_e32 v17, v18, v47
	v_mul_f32_e32 v17, v17, v26
	v_mul_f32_e32 v18, v19, v47
	v_mul_f32_e32 v18, v18, v27
	v_bfe_u32 v19, v17, 16, 1
	v_add3_u32 v17, v17, v19, s36
	v_bfe_u32 v19, v18, 16, 1
	v_lshrrev_b32_e32 v17, 16, v17
	v_add3_u32 v18, v18, v19, s36
	v_and_or_b32 v17, v18, s68, v17
	global_store_dwordx2 v[30:31], v[16:17], off offset:3072 sc1
	global_load_dwordx4 v[16:19], v[88:89], off offset:3072
	s_waitcnt vmcnt(0)
	v_mul_f32_e32 v12, v12, v16
	v_mul_f32_e32 v13, v13, v17
	v_bfe_u32 v20, v12, 16, 1
	v_add3_u32 v12, v12, v20, s36
	v_bfe_u32 v20, v13, 16, 1
	v_lshrrev_b32_e32 v12, 16, v12
	v_add3_u32 v13, v13, v20, s36
	v_and_or_b32 v12, v13, s68, v12
	v_mul_f32_e32 v13, v14, v44
	v_mul_f32_e32 v13, v13, v18
	v_mul_f32_e32 v14, v15, v44
	v_mul_f32_e32 v14, v14, v19
	v_bfe_u32 v15, v13, 16, 1
	v_add3_u32 v13, v13, v15, s36
	v_bfe_u32 v15, v14, 16, 1
	v_lshrrev_b32_e32 v13, 16, v13
	v_add3_u32 v14, v14, v15, s36
	v_and_or_b32 v13, v14, s68, v13
	v_mul_f32_e32 v8, v8, v16
	global_store_dwordx2 v[28:29], v[12:13], off offset:1536 sc1
	v_mul_f32_e32 v9, v9, v17
	v_bfe_u32 v12, v8, 16, 1
	v_add3_u32 v8, v8, v12, s36
	v_bfe_u32 v12, v9, 16, 1
	v_lshrrev_b32_e32 v8, 16, v8
	v_add3_u32 v9, v9, v12, s36
	v_and_or_b32 v8, v9, s68, v8
	v_mul_f32_e32 v9, v10, v45
	v_mul_f32_e32 v9, v9, v18
	v_mul_f32_e32 v10, v11, v45
	v_mul_f32_e32 v10, v10, v19
	v_bfe_u32 v11, v9, 16, 1
	v_add3_u32 v9, v9, v11, s36
	v_bfe_u32 v11, v10, 16, 1
	v_lshrrev_b32_e32 v9, 16, v9
	v_add3_u32 v10, v10, v11, s36
	v_and_or_b32 v9, v10, s68, v9
	v_mul_f32_e32 v4, v4, v16
	global_store_dwordx2 v[28:29], v[8:9], off offset:3584 sc1
	v_mul_f32_e32 v5, v5, v17
	v_bfe_u32 v8, v4, 16, 1
	v_add3_u32 v4, v4, v8, s36
	v_bfe_u32 v8, v5, 16, 1
	v_lshrrev_b32_e32 v4, 16, v4
	v_add3_u32 v5, v5, v8, s36
	v_and_or_b32 v4, v5, s68, v4
	v_mul_f32_e32 v5, v6, v46
	v_mul_f32_e32 v5, v5, v18
	v_mul_f32_e32 v6, v7, v46
	v_mul_f32_e32 v6, v6, v19
	v_bfe_u32 v7, v5, 16, 1
	v_add3_u32 v5, v5, v7, s36
	v_bfe_u32 v7, v6, 16, 1
	v_lshrrev_b32_e32 v5, 16, v5
	v_add3_u32 v6, v6, v7, s36
	v_and_or_b32 v5, v6, s68, v5
	v_mul_f32_e32 v0, v0, v16
	global_store_dwordx2 v[30:31], v[4:5], off offset:1536 sc1
	v_mul_f32_e32 v1, v1, v17
	v_bfe_u32 v4, v0, 16, 1
	v_add3_u32 v0, v0, v4, s36
	v_bfe_u32 v4, v1, 16, 1
	v_lshrrev_b32_e32 v0, 16, v0
	v_add3_u32 v1, v1, v4, s36
	v_and_or_b32 v0, v1, s68, v0
	v_mul_f32_e32 v1, v2, v47
	v_mul_f32_e32 v1, v1, v18
	v_mul_f32_e32 v2, v3, v47
	v_mul_f32_e32 v2, v2, v19
	v_bfe_u32 v3, v1, 16, 1
	v_add3_u32 v1, v1, v3, s36
	v_bfe_u32 v3, v2, 16, 1
	v_lshrrev_b32_e32 v1, 16, v1
	v_add3_u32 v2, v2, v3, s36
	v_and_or_b32 v1, v2, s68, v1
	global_store_dwordx2 v[30:31], v[0:1], off offset:3584 sc1
	s_branch .LBB0_1847
